# v006 + up-epilogue canonicalise removal (store-data hazard padded) + EpiRes second-half residual prefetch (out-proj, cross-out)
# baseline (speedup 1.0000x reference)
; __device__ __forceinline__ unsigned cvt_pk_bf16(float lo, float hi) { unsigned r; asm volatile("v_cvt_pk_bf16_f32 %0, %1, %2" : "=v"(r) : "v"(lo), "v"(hi)); return r; }
;     __device__ __forceinline__ void operator()(const f32x4 (&acc)[2][2][4][2], const Unit& u, int wr, int wc, int fr, int fq) const {
;     ...
;             u32x4 b[4][2]; unsigned long long sv[4];
; #pragma unroll
;             for (int m = 0; m < 4; ++m) { const bf16_t* bp = xb + (size_t)(row0 + ai * HALF + m * 16) * ldc + col0;
; #pragma unroll
;                 for (int bj = 0; bj < 2; ++bj) b[m][bj] = *(const u32x4*)(bp + bj * HALF);
;                 sv[m] = ssin ? ssin[row0 + ai * HALF + m * 16] : 0ull; }
; #pragma unroll
;             for (int m = 0; m < 4; ++m) { const int row = row0 + ai * HALF + m * 16; bf16_t* xp = xb + (size_t)row * ldc + col0;
;                 const float sc = ssin ? 1.0f / ((float)sv[m] * (1.f / (16777216.f * 2048.f)) + 1e-6f) : 1.f;
;                 float q = 0.f;
; #pragma unroll
;                 for (int bj = 0; bj < 2; ++bj) { f32x4 v0, v1;
; #pragma unroll
;                     for (int e = 0; e < 2; ++e) { v0[2 * e] = __builtin_bit_cast(float, b[m][bj][e] << 16); v0[2 * e + 1] = __builtin_bit_cast(float, b[m][bj][e] & 0xffff0000u);
;                                                   v1[2 * e] = __builtin_bit_cast(float, b[m][bj][2 + e] << 16); v1[2 * e + 1] = __builtin_bit_cast(float, b[m][bj][2 + e] & 0xffff0000u); }
;                     v0 += acc[ai][bj][m][0] * sc; v1 += acc[ai][bj][m][1] * sc;
;                     q = __builtin_fmaf(v0[0], v0[0], q); q = __builtin_fmaf(v0[1], v0[1], q); q = __builtin_fmaf(v0[2], v0[2], q); q = __builtin_fmaf(v0[3], v0[3], q);
;                     q = __builtin_fmaf(v1[0], v1[0], q); q = __builtin_fmaf(v1[1], v1[1], q); q = __builtin_fmaf(v1[2], v1[2], q); q = __builtin_fmaf(v1[3], v1[3], q);
;                     if (outf) { float* op = outf + (size_t)row * ldc + col0 + bj * HALF; *(f32x4*)op = v0; *(f32x4*)(op + 4) = v1; }
;                     else { u32x4 w; w.x = cvt_pk_bf16(v0[0], v0[1]); w.y = cvt_pk_bf16(v0[2], v0[3]); w.z = cvt_pk_bf16(v1[0], v1[1]); w.w = cvt_pk_bf16(v1[2], v1[3]); *(u32x4*)(xp + bj * HALF) = w; } }
;                 sq[ai][m] = q; }
.LBB0_530:
	s_lshl_b32 s44, s44, 8
	s_add_i32 s44, s44, s23
	v_lshl_or_b32 v132, s45, 8, v186
	v_or_b32_e32 v172, s44, v184
	v_ashrrev_i32_e32 v133, 31, v132
	v_lshlrev_b64 v[156:157], 1, v[132:133]
	v_ashrrev_i32_e32 v173, 31, v172
	v_lshl_add_u64 v[158:159], s[8:9], 0, v[156:157]
	v_lshlrev_b64 v[194:195], 12, v[172:173]
	v_lshl_add_u64 v[132:133], v[158:159], 0, v[194:195]
	global_load_dwordx4 v[168:171], v[132:133], off
	global_load_dwordx4 v[190:193], v[132:133], off offset:256
	v_or_b32_e32 v132, 16, v172
	v_ashrrev_i32_e32 v133, 31, v132
	v_lshlrev_b64 v[178:179], 12, v[132:133]
	v_lshl_add_u64 v[132:133], v[158:159], 0, v[178:179]
	global_load_dwordx4 v[152:155], v[132:133], off
	global_load_dwordx4 v[148:151], v[132:133], off offset:256
	v_or_b32_e32 v132, 32, v172
	v_ashrrev_i32_e32 v133, 31, v132
	v_lshlrev_b64 v[176:177], 12, v[132:133]
	v_lshl_add_u64 v[132:133], v[158:159], 0, v[176:177]
	global_load_dwordx4 v[144:147], v[132:133], off
	global_load_dwordx4 v[140:143], v[132:133], off offset:256
	v_or_b32_e32 v132, 48, v172
	v_ashrrev_i32_e32 v133, 31, v132
	v_lshlrev_b64 v[174:175], 12, v[132:133]
	v_lshl_add_u64 v[132:133], v[158:159], 0, v[174:175]
	global_load_dwordx4 v[136:139], v[132:133], off
	s_nop 0
	global_load_dwordx4 v[132:135], v[132:133], off offset:256
	v_lshlrev_b64 v[208:209], 12, v[172:173]
	v_lshl_add_u64 v[208:209], v[158:159], 0, v[208:209]
	v_mov_b32_e32 v212, 0x10000
	v_mov_b32_e32 v213, 0
	v_mov_b32_e32 v214, 0x80000
	v_mov_b32_e32 v215, 0
	v_lshl_add_u64 v[210:211], v[208:209], 0, v[214:215]
	global_load_dwordx4 v[218:221], v[210:211], off
	global_load_dwordx4 v[222:225], v[210:211], off offset:256
	v_lshl_add_u64 v[210:211], v[210:211], 0, v[212:213]
	global_load_dwordx4 v[226:229], v[210:211], off
	global_load_dwordx4 v[230:233], v[210:211], off offset:256
	v_lshl_add_u64 v[210:211], v[210:211], 0, v[212:213]
	global_load_dwordx4 v[234:237], v[210:211], off
	global_load_dwordx4 v[238:241], v[210:211], off offset:256
	v_lshl_add_u64 v[210:211], v[210:211], 0, v[212:213]
	global_load_dwordx4 v[242:245], v[210:211], off
	global_load_dwordx4 v[246:249], v[210:211], off offset:256
	v_lshl_add_u64 v[194:195], s[8:9], 0, v[194:195]
	v_lshl_add_u64 v[194:195], v[194:195], 0, v[156:157]
	v_cmp_lt_i32_e32 vcc, 1, v183
	s_waitcnt vmcnt(15)
	v_lshlrev_b32_e32 v196, 16, v168
	v_and_b32_e32 v197, 0xffff0000, v168
	v_lshlrev_b32_e32 v198, 16, v170
	v_and_b32_e32 v199, 0xffff0000, v170
	v_lshlrev_b32_e32 v168, 16, v169
	v_and_b32_e32 v169, 0xffff0000, v169
	v_lshlrev_b32_e32 v170, 16, v171
	v_and_b32_e32 v171, 0xffff0000, v171
	v_pk_add_f32 v[128:129], v[128:129], v[196:197]
	v_pk_add_f32 v[130:131], v[130:131], v[168:169]
	v_pk_add_f32 v[168:169], v[126:127], v[170:171]
	v_pk_add_f32 v[170:171], v[124:125], v[198:199]
	v_fma_f32 v124, v128, v128, 0
	v_fmac_f32_e32 v124, v129, v129
	v_fmac_f32_e32 v124, v130, v130
	v_fmac_f32_e32 v124, v131, v131
	v_fmac_f32_e32 v124, v170, v170
	v_fmac_f32_e32 v124, v171, v171
	v_cvt_pk_bf16_f32 v126, v128, v129
	v_cvt_pk_bf16_f32 v127, v130, v131
	v_fmac_f32_e32 v124, v168, v168
	v_cvt_pk_bf16_f32 v128, v170, v171
	v_cvt_pk_bf16_f32 v129, v168, v169
	global_store_dwordx4 v[194:195], v[126:129], off
	v_fmac_f32_e32 v124, v169, v169
	s_waitcnt vmcnt(15)
	v_lshlrev_b32_e32 v130, 16, v191
	v_lshlrev_b32_e32 v126, 16, v190
	v_and_b32_e32 v127, 0xffff0000, v190
	v_pk_add_f32 v[120:121], v[120:121], v[126:127]
	v_and_b32_e32 v131, 0xffff0000, v191
	v_fmac_f32_e32 v124, v120, v120
	v_pk_add_f32 v[122:123], v[122:123], v[130:131]
	v_fmac_f32_e32 v124, v121, v121
	v_lshlrev_b32_e32 v128, 16, v192
	v_and_b32_e32 v129, 0xffff0000, v192
	v_lshlrev_b32_e32 v168, 16, v193
	v_and_b32_e32 v169, 0xffff0000, v193
	v_fmac_f32_e32 v124, v122, v122
	v_pk_add_f32 v[126:127], v[118:119], v[168:169]
	v_pk_add_f32 v[118:119], v[116:117], v[128:129]
	v_fmac_f32_e32 v124, v123, v123
	v_fmac_f32_e32 v124, v118, v118
	v_fmac_f32_e32 v124, v119, v119
	v_cvt_pk_bf16_f32 v116, v120, v121
	v_cvt_pk_bf16_f32 v117, v122, v123
	v_cvt_pk_bf16_f32 v118, v118, v119
	v_cvt_pk_bf16_f32 v119, v126, v127
	v_fmac_f32_e32 v124, v126, v126
	global_store_dwordx4 v[194:195], v[116:119], off offset:256
	v_fmac_f32_e32 v124, v127, v127
	s_waitcnt vmcnt(15)
	v_lshlrev_b32_e32 v120, 16, v154
	v_lshlrev_b32_e32 v118, 16, v152
	v_and_b32_e32 v119, 0xffff0000, v152
	v_and_b32_e32 v121, 0xffff0000, v154
	v_lshlrev_b32_e32 v126, 16, v155
	v_and_b32_e32 v127, 0xffff0000, v155
	v_pk_add_f32 v[112:113], v[112:113], v[118:119]
	v_lshlrev_b32_e32 v122, 16, v153
	v_and_b32_e32 v123, 0xffff0000, v153
	v_pk_add_f32 v[118:119], v[110:111], v[126:127]
	v_pk_add_f32 v[110:111], v[108:109], v[120:121]
	v_fma_f32 v120, v112, v112, 0
	v_pk_add_f32 v[114:115], v[114:115], v[122:123]
	v_fmac_f32_e32 v120, v113, v113
	v_fmac_f32_e32 v120, v114, v114
	v_fmac_f32_e32 v120, v115, v115
	v_lshl_add_u64 v[116:117], s[8:9], 0, v[178:179]
	v_fmac_f32_e32 v120, v110, v110
	v_lshl_add_u64 v[116:117], v[116:117], 0, v[156:157]
	v_fmac_f32_e32 v120, v111, v111
	v_cvt_pk_bf16_f32 v108, v112, v113
	v_cvt_pk_bf16_f32 v109, v114, v115
	v_fmac_f32_e32 v120, v118, v118
	v_cvt_pk_bf16_f32 v110, v110, v111
	v_cvt_pk_bf16_f32 v111, v118, v119
	global_store_dwordx4 v[116:117], v[108:111], off
	v_fmac_f32_e32 v120, v119, v119
	s_waitcnt vmcnt(15)
; __device__ __forceinline__ unsigned cvt_pk_bf16(float lo, float hi) { unsigned r; asm volatile("v_cvt_pk_bf16_f32 %0, %1, %2" : "=v"(r) : "v"(lo), "v"(hi)); return r; }
;     __device__ __forceinline__ void operator()(const f32x4 (&acc)[2][2][4][2], const Unit& u, int wr, int wc, int fr, int fq) const {
;     ...
;             for (int m = 0; m < 4; ++m) { const int row = row0 + ai * HALF + m * 16; bf16_t* xp = xb + (size_t)row * ldc + col0;
;                 const float sc = ssin ? 1.0f / ((float)sv[m] * (1.f / (16777216.f * 2048.f)) + 1e-6f) : 1.f;
;                 float q = 0.f;
; #pragma unroll
;                 for (int bj = 0; bj < 2; ++bj) { f32x4 v0, v1;
; #pragma unroll
;                     for (int e = 0; e < 2; ++e) { v0[2 * e] = __builtin_bit_cast(float, b[m][bj][e] << 16); v0[2 * e + 1] = __builtin_bit_cast(float, b[m][bj][e] & 0xffff0000u);
;                                                   v1[2 * e] = __builtin_bit_cast(float, b[m][bj][2 + e] << 16); v1[2 * e + 1] = __builtin_bit_cast(float, b[m][bj][2 + e] & 0xffff0000u); }
;                     v0 += acc[ai][bj][m][0] * sc; v1 += acc[ai][bj][m][1] * sc;
;                     q = __builtin_fmaf(v0[0], v0[0], q); q = __builtin_fmaf(v0[1], v0[1], q); q = __builtin_fmaf(v0[2], v0[2], q); q = __builtin_fmaf(v0[3], v0[3], q);
;                     q = __builtin_fmaf(v1[0], v1[0], q); q = __builtin_fmaf(v1[1], v1[1], q); q = __builtin_fmaf(v1[2], v1[2], q); q = __builtin_fmaf(v1[3], v1[3], q);
;                     if (outf) { float* op = outf + (size_t)row * ldc + col0 + bj * HALF; *(f32x4*)op = v0; *(f32x4*)(op + 4) = v1; }
;                     else { u32x4 w; w.x = cvt_pk_bf16(v0[0], v0[1]); w.y = cvt_pk_bf16(v0[2], v0[3]); w.z = cvt_pk_bf16(v1[0], v1[1]); w.w = cvt_pk_bf16(v1[2], v1[3]); *(u32x4*)(xp + bj * HALF) = w; } }
;                 sq[ai][m] = q; }
;             asm volatile("" ::: "memory");
; #pragma unroll
;             for (int m = 0; m < 4; ++m) { float q = sq[ai][m]; q = fq_sum(q); sq[ai][m] = q; }
;             const float v = fq == 0 ? sq[ai][0] : (fq == 1 ? sq[ai][1] : (fq == 2 ? sq[ai][2] : sq[ai][3]));
	v_lshlrev_b32_e32 v112, 16, v149
	v_lshlrev_b32_e32 v108, 16, v148
	v_and_b32_e32 v109, 0xffff0000, v148
	v_pk_add_f32 v[104:105], v[104:105], v[108:109]
	v_and_b32_e32 v113, 0xffff0000, v149
	v_fmac_f32_e32 v120, v104, v104
	v_pk_add_f32 v[106:107], v[106:107], v[112:113]
	v_fmac_f32_e32 v120, v105, v105
	v_lshlrev_b32_e32 v110, 16, v150
	v_and_b32_e32 v111, 0xffff0000, v150
	v_lshlrev_b32_e32 v114, 16, v151
	v_and_b32_e32 v115, 0xffff0000, v151
	v_fmac_f32_e32 v120, v106, v106
	v_pk_add_f32 v[108:109], v[102:103], v[114:115]
	v_pk_add_f32 v[102:103], v[100:101], v[110:111]
	v_fmac_f32_e32 v120, v107, v107
	v_fmac_f32_e32 v120, v102, v102
	v_fmac_f32_e32 v120, v103, v103
	v_cvt_pk_bf16_f32 v100, v104, v105
	v_cvt_pk_bf16_f32 v101, v106, v107
	v_cvt_pk_bf16_f32 v102, v102, v103
	v_cvt_pk_bf16_f32 v103, v108, v109
	v_fmac_f32_e32 v120, v108, v108
	global_store_dwordx4 v[116:117], v[100:103], off offset:256
	v_fmac_f32_e32 v120, v109, v109
	s_waitcnt vmcnt(15)
	v_lshlrev_b32_e32 v104, 16, v146
	v_lshlrev_b32_e32 v102, 16, v144
	v_and_b32_e32 v103, 0xffff0000, v144
	v_and_b32_e32 v105, 0xffff0000, v146
	v_lshlrev_b32_e32 v108, 16, v147
	v_and_b32_e32 v109, 0xffff0000, v147
	v_pk_add_f32 v[96:97], v[96:97], v[102:103]
	v_lshlrev_b32_e32 v106, 16, v145
	v_and_b32_e32 v107, 0xffff0000, v145
	v_pk_add_f32 v[102:103], v[94:95], v[108:109]
	v_pk_add_f32 v[94:95], v[92:93], v[104:105]
	v_fma_f32 v104, v96, v96, 0
	v_pk_add_f32 v[98:99], v[98:99], v[106:107]
	v_fmac_f32_e32 v104, v97, v97
	v_fmac_f32_e32 v104, v98, v98
	v_fmac_f32_e32 v104, v99, v99
	v_lshl_add_u64 v[100:101], s[8:9], 0, v[176:177]
	v_fmac_f32_e32 v104, v94, v94
	v_lshl_add_u64 v[100:101], v[100:101], 0, v[156:157]
	v_fmac_f32_e32 v104, v95, v95
	v_cvt_pk_bf16_f32 v92, v96, v97
	v_cvt_pk_bf16_f32 v93, v98, v99
	v_fmac_f32_e32 v104, v102, v102
	v_cvt_pk_bf16_f32 v94, v94, v95
	v_cvt_pk_bf16_f32 v95, v102, v103
	global_store_dwordx4 v[100:101], v[92:95], off
	v_fmac_f32_e32 v104, v103, v103
	s_waitcnt vmcnt(15)
	v_lshlrev_b32_e32 v96, 16, v141
	v_lshlrev_b32_e32 v92, 16, v140
	v_and_b32_e32 v93, 0xffff0000, v140
	v_pk_add_f32 v[88:89], v[88:89], v[92:93]
	v_and_b32_e32 v97, 0xffff0000, v141
	v_fmac_f32_e32 v104, v88, v88
	v_pk_add_f32 v[90:91], v[90:91], v[96:97]
	v_fmac_f32_e32 v104, v89, v89
	v_lshlrev_b32_e32 v94, 16, v142
	v_and_b32_e32 v95, 0xffff0000, v142
	v_lshlrev_b32_e32 v98, 16, v143
	v_and_b32_e32 v99, 0xffff0000, v143
	v_fmac_f32_e32 v104, v90, v90
	v_pk_add_f32 v[92:93], v[86:87], v[98:99]
	v_pk_add_f32 v[86:87], v[84:85], v[94:95]
	v_fmac_f32_e32 v104, v91, v91
	v_fmac_f32_e32 v104, v86, v86
	v_fmac_f32_e32 v104, v87, v87
	v_cvt_pk_bf16_f32 v84, v88, v89
	v_cvt_pk_bf16_f32 v85, v90, v91
	v_cvt_pk_bf16_f32 v86, v86, v87
	v_cvt_pk_bf16_f32 v87, v92, v93
	v_fmac_f32_e32 v104, v92, v92
	global_store_dwordx4 v[100:101], v[84:87], off offset:256
	v_fmac_f32_e32 v104, v93, v93
	s_waitcnt vmcnt(15)
	v_lshlrev_b32_e32 v88, 16, v138
	v_lshlrev_b32_e32 v86, 16, v136
	v_and_b32_e32 v87, 0xffff0000, v136
	v_and_b32_e32 v89, 0xffff0000, v138
	v_lshlrev_b32_e32 v92, 16, v139
	v_and_b32_e32 v93, 0xffff0000, v139
	v_pk_add_f32 v[80:81], v[80:81], v[86:87]
	v_lshlrev_b32_e32 v90, 16, v137
	v_and_b32_e32 v91, 0xffff0000, v137
	v_pk_add_f32 v[86:87], v[78:79], v[92:93]
	v_pk_add_f32 v[78:79], v[76:77], v[88:89]
	v_fma_f32 v88, v80, v80, 0
	v_pk_add_f32 v[82:83], v[82:83], v[90:91]
	v_fmac_f32_e32 v88, v81, v81
	v_fmac_f32_e32 v88, v82, v82
	v_fmac_f32_e32 v88, v83, v83
	v_lshl_add_u64 v[84:85], s[8:9], 0, v[174:175]
	v_fmac_f32_e32 v88, v78, v78
	v_lshl_add_u64 v[84:85], v[84:85], 0, v[156:157]
	v_fmac_f32_e32 v88, v79, v79
	v_cvt_pk_bf16_f32 v76, v80, v81
	v_cvt_pk_bf16_f32 v77, v82, v83
	v_fmac_f32_e32 v88, v86, v86
	v_cvt_pk_bf16_f32 v78, v78, v79
	v_cvt_pk_bf16_f32 v79, v86, v87
	global_store_dwordx4 v[84:85], v[76:79], off
	v_fmac_f32_e32 v88, v87, v87
	s_waitcnt vmcnt(15)
	v_lshlrev_b32_e32 v80, 16, v133
	v_lshlrev_b32_e32 v76, 16, v132
	v_and_b32_e32 v77, 0xffff0000, v132
	v_pk_add_f32 v[72:73], v[72:73], v[76:77]
	v_and_b32_e32 v81, 0xffff0000, v133
	v_fmac_f32_e32 v88, v72, v72
	v_pk_add_f32 v[74:75], v[74:75], v[80:81]
	v_fmac_f32_e32 v88, v73, v73
	v_lshlrev_b32_e32 v78, 16, v134
	v_and_b32_e32 v79, 0xffff0000, v134
	v_lshlrev_b32_e32 v82, 16, v135
	v_and_b32_e32 v83, 0xffff0000, v135
	v_fmac_f32_e32 v88, v74, v74
	v_pk_add_f32 v[76:77], v[70:71], v[82:83]
	v_pk_add_f32 v[70:71], v[68:69], v[78:79]
	v_fmac_f32_e32 v88, v75, v75
	v_fmac_f32_e32 v88, v70, v70
	v_cvt_pk_bf16_f32 v68, v72, v73
	v_fmac_f32_e32 v88, v71, v71
	v_cvt_pk_bf16_f32 v69, v74, v75
	v_cvt_pk_bf16_f32 v70, v70, v71
	v_cvt_pk_bf16_f32 v71, v76, v77
	global_store_dwordx4 v[84:85], v[68:71], off offset:256
	v_fmac_f32_e32 v88, v76, v76
	v_fmac_f32_e32 v88, v77, v77
	v_mov_b32_e32 v68, v124
	s_nop 1
	v_permlane16_swap_b32_e32 v124, v68
	v_add_f32_e32 v70, v124, v68
	v_mov_b32_e32 v68, v120
	s_nop 1
	v_permlane16_swap_b32_e32 v120, v68
	v_add_f32_e32 v72, v120, v68
	v_mov_b32_e32 v68, v104
	s_nop 1
	v_permlane16_swap_b32_e32 v104, v68
	v_add_f32_e32 v74, v104, v68
	v_mov_b32_e32 v68, v88
	s_nop 1
	v_permlane16_swap_b32_e32 v88, v68
	v_add_f32_e32 v68, v88, v68
	v_mov_b32_e32 v71, v70
	v_mov_b32_e32 v73, v72
	v_mov_b32_e32 v75, v74
	v_mov_b32_e32 v69, v68
	v_permlane32_swap_b32_e32 v70, v71
	v_permlane32_swap_b32_e32 v72, v73
	v_permlane32_swap_b32_e32 v74, v75
	v_permlane32_swap_b32_e32 v68, v69
	s_and_saveexec_b64 s[0:1], vcc
	s_xor_b64 s[0:1], exec, s[0:1]
	s_cbranch_execz .LBB0_536
	v_cmp_lt_i32_e32 vcc, 2, v183
	s_and_saveexec_b64 s[6:7], vcc
	s_xor_b64 s[6:7], exec, s[6:7]
	s_andn2_saveexec_b64 s[6:7], s[6:7]
	v_mov_b32_e32 v68, v74
	v_mov_b32_e32 v69, v75
	s_or_b64 exec, exec, s[6:7]

;     __device__ __forceinline__ void operator()(const f32x4 (&acc)[2][2][4][2], const Unit& u, int wr, int wc, int fr, int fq) const {
;     ...
;             for (int m = 0; m < 4; ++m) { const bf16_t* bp = xb + (size_t)(row0 + ai * HALF + m * 16) * ldc + col0;
; #pragma unroll
;                 for (int bj = 0; bj < 2; ++bj) b[m][bj] = *(const u32x4*)(bp + bj * HALF);
;                 sv[m] = ssin ? ssin[row0 + ai * HALF + m * 16] : 0ull; }
; #pragma unroll
;             for (int m = 0; m < 4; ++m) { const int row = row0 + ai * HALF + m * 16; bf16_t* xp = xb + (size_t)row * ldc + col0;
;                 const float sc = ssin ? 1.0f / ((float)sv[m] * (1.f / (16777216.f * 2048.f)) + 1e-6f) : 1.f;
;                 float q = 0.f;
; #pragma unroll
;                 for (int bj = 0; bj < 2; ++bj) { f32x4 v0, v1;
; #pragma unroll
;                     for (int e = 0; e < 2; ++e) { v0[2 * e] = __builtin_bit_cast(float, b[m][bj][e] << 16); v0[2 * e + 1] = __builtin_bit_cast(float, b[m][bj][e] & 0xffff0000u);
;                                                   v1[2 * e] = __builtin_bit_cast(float, b[m][bj][2 + e] << 16); v1[2 * e + 1] = __builtin_bit_cast(float, b[m][bj][2 + e] & 0xffff0000u); }
;                     v0 += acc[ai][bj][m][0] * sc; v1 += acc[ai][bj][m][1] * sc;
;                     q = __builtin_fmaf(v0[0], v0[0], q); q = __builtin_fmaf(v0[1], v0[1], q); q = __builtin_fmaf(v0[2], v0[2], q); q = __builtin_fmaf(v0[3], v0[3], q);
;                     q = __builtin_fmaf(v1[0], v1[0], q); q = __builtin_fmaf(v1[1], v1[1], q); q = __builtin_fmaf(v1[2], v1[2], q); q = __builtin_fmaf(v1[3], v1[3], q);
;                     if (outf) { float* op = outf + (size_t)row * ldc + col0 + bj * HALF; *(f32x4*)op = v0; *(f32x4*)(op + 4) = v1; }
;                     else { u32x4 w; w.x = cvt_pk_bf16(v0[0], v0[1]); w.y = cvt_pk_bf16(v0[2], v0[3]); w.z = cvt_pk_bf16(v1[0], v1[1]); w.w = cvt_pk_bf16(v1[2], v1[3]); *(u32x4*)(xp + bj * HALF) = w; } }
;                 sq[ai][m] = q; }
;             asm volatile("" ::: "memory");
; #pragma unroll
;             for (int m = 0; m < 4; ++m) { float q = sq[ai][m]; q = fq_sum(q); sq[ai][m] = q; }
;             const float v = fq == 0 ? sq[ai][0] : (fq == 1 ? sq[ai][1] : (fq == 2 ? sq[ai][2] : sq[ai][3]));
;             atomicAdd(ssout + (u.pm * BM + wr * 64 + ai * HALF + fq * 16 + fr), (unsigned long long)(v * 16777216.f));
.LBB0_540:
	s_or_b64 exec, exec, s[0:1]
	v_add_f32_e32 v70, v68, v69
	v_mul_f32_e32 v70, 0x4b800000, v70
	v_trunc_f32_e32 v70, v70
	v_mul_f32_e32 v71, 0x2f800000, v70
	v_floor_f32_e32 v71, v71
	v_fmac_f32_e32 v70, 0xcf800000, v71
	v_cvt_u32_f32_e32 v70, v70
	v_cvt_u32_f32_e32 v71, v71
	v_or_b32_e32 v92, s44, v185
	v_ashrrev_i32_e32 v93, 31, v92
	v_lshl_add_u64 v[68:69], v[92:93], 3, s[10:11]
	global_atomic_add_x2 v[68:69], v[70:71], off
	v_lshlrev_b64 v[68:69], 12, v[172:173]
	s_mov_b64 s[0:1], 0x80000
	v_lshl_add_u64 v[108:109], v[68:69], 0, s[0:1]
	v_lshl_add_u64 v[70:71], v[158:159], 0, v[108:109]
	s_waitcnt vmcnt(8)
	v_mov_b64_e32 v[100:101], v[218:219]
	v_mov_b64_e32 v[102:103], v[220:221]
	v_mov_b64_e32 v[104:105], v[222:223]
	v_mov_b64_e32 v[106:107], v[224:225]
	s_mov_b64 s[0:1], 0x90000
	v_lshl_add_u64 v[98:99], v[68:69], 0, s[0:1]
	v_lshl_add_u64 v[70:71], v[158:159], 0, v[98:99]
	v_mov_b64_e32 v[88:89], v[226:227]
	v_mov_b64_e32 v[90:91], v[228:229]
	v_mov_b64_e32 v[84:85], v[230:231]
	v_mov_b64_e32 v[86:87], v[232:233]
	s_mov_b64 s[0:1], 0xa0000
	v_lshl_add_u64 v[96:97], v[68:69], 0, s[0:1]
	v_lshl_add_u64 v[70:71], v[158:159], 0, v[96:97]
	v_mov_b64_e32 v[80:81], v[234:235]
	v_mov_b64_e32 v[82:83], v[236:237]
	v_mov_b64_e32 v[76:77], v[238:239]
	v_mov_b64_e32 v[78:79], v[240:241]
	s_mov_b64 s[0:1], 0xb0000
	v_lshl_add_u64 v[94:95], v[68:69], 0, s[0:1]
	v_lshl_add_u64 v[68:69], v[158:159], 0, v[94:95]
	v_mov_b64_e32 v[72:73], v[242:243]
	v_mov_b64_e32 v[74:75], v[244:245]
	s_nop 0
	v_mov_b64_e32 v[68:69], v[246:247]
	v_mov_b64_e32 v[70:71], v[248:249]
	v_lshl_add_u64 v[108:109], s[8:9], 0, v[108:109]
	v_lshl_add_u64 v[108:109], v[108:109], 0, v[156:157]
	v_readlane_b32 s46, v254, 18
	v_cmp_lt_i32_e32 vcc, 1, v183
	v_readlane_b32 s47, v254, 19
	s_waitcnt vmcnt(7)
	v_lshlrev_b32_e32 v110, 16, v100
	v_and_b32_e32 v111, 0xffff0000, v100
	v_lshlrev_b32_e32 v112, 16, v102
	v_and_b32_e32 v113, 0xffff0000, v102
	v_lshlrev_b32_e32 v100, 16, v101
	v_and_b32_e32 v101, 0xffff0000, v101
	v_lshlrev_b32_e32 v102, 16, v103
	v_and_b32_e32 v103, 0xffff0000, v103
	v_pk_add_f32 v[64:65], v[64:65], v[110:111]
	v_pk_add_f32 v[66:67], v[66:67], v[100:101]
	v_pk_add_f32 v[100:101], v[62:63], v[102:103]
	v_pk_add_f32 v[102:103], v[60:61], v[112:113]
	v_fma_f32 v60, v64, v64, 0
	v_fmac_f32_e32 v60, v65, v65
	v_fmac_f32_e32 v60, v66, v66
	v_fmac_f32_e32 v60, v67, v67
	v_fmac_f32_e32 v60, v102, v102
	v_fmac_f32_e32 v60, v103, v103
	v_cvt_pk_bf16_f32 v62, v64, v65
	v_cvt_pk_bf16_f32 v63, v66, v67
	v_fmac_f32_e32 v60, v100, v100
	v_cvt_pk_bf16_f32 v64, v102, v103
	v_cvt_pk_bf16_f32 v65, v100, v101
	global_store_dwordx4 v[108:109], v[62:65], off
	v_fmac_f32_e32 v60, v101, v101
	s_waitcnt vmcnt(7)
	v_lshlrev_b32_e32 v66, 16, v105
	v_lshlrev_b32_e32 v62, 16, v104
	v_and_b32_e32 v63, 0xffff0000, v104
	v_pk_add_f32 v[56:57], v[56:57], v[62:63]
	v_and_b32_e32 v67, 0xffff0000, v105
	v_fmac_f32_e32 v60, v56, v56
	v_pk_add_f32 v[58:59], v[58:59], v[66:67]
	v_fmac_f32_e32 v60, v57, v57
	v_lshlrev_b32_e32 v64, 16, v106
	v_and_b32_e32 v65, 0xffff0000, v106
	v_lshlrev_b32_e32 v100, 16, v107
	v_and_b32_e32 v101, 0xffff0000, v107
	v_fmac_f32_e32 v60, v58, v58
	v_pk_add_f32 v[62:63], v[54:55], v[100:101]
	v_pk_add_f32 v[54:55], v[52:53], v[64:65]
	v_fmac_f32_e32 v60, v59, v59
	v_fmac_f32_e32 v60, v54, v54
	v_fmac_f32_e32 v60, v55, v55
	v_cvt_pk_bf16_f32 v52, v56, v57
	v_cvt_pk_bf16_f32 v53, v58, v59
	v_cvt_pk_bf16_f32 v54, v54, v55
	v_cvt_pk_bf16_f32 v55, v62, v63
	global_store_dwordx4 v[108:109], v[52:55], off offset:256
	s_waitcnt vmcnt(7)
	v_lshlrev_b32_e32 v56, 16, v90
	v_and_b32_e32 v57, 0xffff0000, v90
	v_lshlrev_b32_e32 v54, 16, v88
	v_and_b32_e32 v55, 0xffff0000, v88
	v_pk_add_f32 v[48:49], v[48:49], v[54:55]
	v_lshlrev_b32_e32 v58, 16, v89
	v_and_b32_e32 v59, 0xffff0000, v89
	v_pk_add_f32 v[56:57], v[44:45], v[56:57]
	v_fma_f32 v44, v48, v48, 0
	v_pk_add_f32 v[50:51], v[50:51], v[58:59]
	v_fmac_f32_e32 v44, v49, v49
	v_fmac_f32_e32 v44, v50, v50
	v_fmac_f32_e32 v60, v62, v62
	v_fmac_f32_e32 v44, v51, v51
	v_fmac_f32_e32 v60, v63, v63
	v_lshl_add_u64 v[52:53], s[8:9], 0, v[98:99]
	v_lshlrev_b32_e32 v62, 16, v91
	v_and_b32_e32 v63, 0xffff0000, v91
	v_fmac_f32_e32 v44, v56, v56
	v_lshl_add_u64 v[52:53], v[52:53], 0, v[156:157]
	v_pk_add_f32 v[54:55], v[46:47], v[62:63]
	v_fmac_f32_e32 v44, v57, v57
	v_cvt_pk_bf16_f32 v46, v48, v49
	v_cvt_pk_bf16_f32 v47, v50, v51
	v_fmac_f32_e32 v44, v54, v54
	v_cvt_pk_bf16_f32 v48, v56, v57
	v_cvt_pk_bf16_f32 v49, v54, v55
	global_store_dwordx4 v[52:53], v[46:49], off
	v_fmac_f32_e32 v44, v55, v55
	s_waitcnt vmcnt(7)
; __device__ __forceinline__ unsigned cvt_pk_bf16(float lo, float hi) { unsigned r; asm volatile("v_cvt_pk_bf16_f32 %0, %1, %2" : "=v"(r) : "v"(lo), "v"(hi)); return r; }
;     __device__ __forceinline__ void operator()(const f32x4 (&acc)[2][2][4][2], const Unit& u, int wr, int wc, int fr, int fq) const {
;     ...
;             for (int m = 0; m < 4; ++m) { const int row = row0 + ai * HALF + m * 16; bf16_t* xp = xb + (size_t)row * ldc + col0;
;                 const float sc = ssin ? 1.0f / ((float)sv[m] * (1.f / (16777216.f * 2048.f)) + 1e-6f) : 1.f;
;                 float q = 0.f;
; #pragma unroll
;                 for (int bj = 0; bj < 2; ++bj) { f32x4 v0, v1;
; #pragma unroll
;                     for (int e = 0; e < 2; ++e) { v0[2 * e] = __builtin_bit_cast(float, b[m][bj][e] << 16); v0[2 * e + 1] = __builtin_bit_cast(float, b[m][bj][e] & 0xffff0000u);
;                                                   v1[2 * e] = __builtin_bit_cast(float, b[m][bj][2 + e] << 16); v1[2 * e + 1] = __builtin_bit_cast(float, b[m][bj][2 + e] & 0xffff0000u); }
;                     v0 += acc[ai][bj][m][0] * sc; v1 += acc[ai][bj][m][1] * sc;
;                     q = __builtin_fmaf(v0[0], v0[0], q); q = __builtin_fmaf(v0[1], v0[1], q); q = __builtin_fmaf(v0[2], v0[2], q); q = __builtin_fmaf(v0[3], v0[3], q);
;                     q = __builtin_fmaf(v1[0], v1[0], q); q = __builtin_fmaf(v1[1], v1[1], q); q = __builtin_fmaf(v1[2], v1[2], q); q = __builtin_fmaf(v1[3], v1[3], q);
;                     if (outf) { float* op = outf + (size_t)row * ldc + col0 + bj * HALF; *(f32x4*)op = v0; *(f32x4*)(op + 4) = v1; }
;                     else { u32x4 w; w.x = cvt_pk_bf16(v0[0], v0[1]); w.y = cvt_pk_bf16(v0[2], v0[3]); w.z = cvt_pk_bf16(v1[0], v1[1]); w.w = cvt_pk_bf16(v1[2], v1[3]); *(u32x4*)(xp + bj * HALF) = w; } }
;                 sq[ai][m] = q; }
;             asm volatile("" ::: "memory");
; #pragma unroll
;             for (int m = 0; m < 4; ++m) { float q = sq[ai][m]; q = fq_sum(q); sq[ai][m] = q; }
;             const float v = fq == 0 ? sq[ai][0] : (fq == 1 ? sq[ai][1] : (fq == 2 ? sq[ai][2] : sq[ai][3]));
	v_lshlrev_b32_e32 v50, 16, v85
	v_lshlrev_b32_e32 v46, 16, v84
	v_and_b32_e32 v47, 0xffff0000, v84
	v_pk_add_f32 v[40:41], v[40:41], v[46:47]
	v_and_b32_e32 v51, 0xffff0000, v85
	v_fmac_f32_e32 v44, v40, v40
	v_pk_add_f32 v[42:43], v[42:43], v[50:51]
	v_fmac_f32_e32 v44, v41, v41
	v_lshlrev_b32_e32 v48, 16, v86
	v_and_b32_e32 v49, 0xffff0000, v86
	v_lshlrev_b32_e32 v54, 16, v87
	v_and_b32_e32 v55, 0xffff0000, v87
	v_fmac_f32_e32 v44, v42, v42
	v_pk_add_f32 v[46:47], v[38:39], v[54:55]
	v_pk_add_f32 v[38:39], v[36:37], v[48:49]
	v_fmac_f32_e32 v44, v43, v43
	v_fmac_f32_e32 v44, v38, v38
	v_fmac_f32_e32 v44, v39, v39
	v_cvt_pk_bf16_f32 v36, v40, v41
	v_cvt_pk_bf16_f32 v37, v42, v43
	v_cvt_pk_bf16_f32 v38, v38, v39
	v_cvt_pk_bf16_f32 v39, v46, v47
	v_fmac_f32_e32 v44, v46, v46
	global_store_dwordx4 v[52:53], v[36:39], off offset:256
	v_fmac_f32_e32 v44, v47, v47
	s_waitcnt vmcnt(7)
	v_lshlrev_b32_e32 v40, 16, v82
	v_lshlrev_b32_e32 v38, 16, v80
	v_and_b32_e32 v39, 0xffff0000, v80
	v_and_b32_e32 v41, 0xffff0000, v82
	v_lshlrev_b32_e32 v46, 16, v83
	v_and_b32_e32 v47, 0xffff0000, v83
	v_pk_add_f32 v[32:33], v[32:33], v[38:39]
	v_lshlrev_b32_e32 v42, 16, v81
	v_and_b32_e32 v43, 0xffff0000, v81
	v_pk_add_f32 v[38:39], v[30:31], v[46:47]
	v_pk_add_f32 v[30:31], v[28:29], v[40:41]
	v_fma_f32 v40, v32, v32, 0
	v_pk_add_f32 v[34:35], v[34:35], v[42:43]
	v_fmac_f32_e32 v40, v33, v33
	v_fmac_f32_e32 v40, v34, v34
	v_fmac_f32_e32 v40, v35, v35
	v_lshl_add_u64 v[36:37], s[8:9], 0, v[96:97]
	v_fmac_f32_e32 v40, v30, v30
	v_lshl_add_u64 v[36:37], v[36:37], 0, v[156:157]
	v_fmac_f32_e32 v40, v31, v31
	v_cvt_pk_bf16_f32 v28, v32, v33
	v_cvt_pk_bf16_f32 v29, v34, v35
	v_fmac_f32_e32 v40, v38, v38
	v_cvt_pk_bf16_f32 v30, v30, v31
	v_cvt_pk_bf16_f32 v31, v38, v39
	global_store_dwordx4 v[36:37], v[28:31], off
	v_fmac_f32_e32 v40, v39, v39
	s_waitcnt vmcnt(7)
	v_lshlrev_b32_e32 v32, 16, v77
	v_lshlrev_b32_e32 v28, 16, v76
	v_and_b32_e32 v29, 0xffff0000, v76
	v_pk_add_f32 v[24:25], v[24:25], v[28:29]
	v_and_b32_e32 v33, 0xffff0000, v77
	v_fmac_f32_e32 v40, v24, v24
	v_pk_add_f32 v[26:27], v[26:27], v[32:33]
	v_fmac_f32_e32 v40, v25, v25
	v_lshlrev_b32_e32 v30, 16, v78
	v_and_b32_e32 v31, 0xffff0000, v78
	v_lshlrev_b32_e32 v34, 16, v79
	v_and_b32_e32 v35, 0xffff0000, v79
	v_fmac_f32_e32 v40, v26, v26
	v_pk_add_f32 v[28:29], v[22:23], v[34:35]
	v_pk_add_f32 v[22:23], v[20:21], v[30:31]
	v_fmac_f32_e32 v40, v27, v27
	v_fmac_f32_e32 v40, v22, v22
	v_fmac_f32_e32 v40, v23, v23
	v_cvt_pk_bf16_f32 v20, v24, v25
	v_cvt_pk_bf16_f32 v21, v26, v27
	v_cvt_pk_bf16_f32 v22, v22, v23
	v_cvt_pk_bf16_f32 v23, v28, v29
	v_fmac_f32_e32 v40, v28, v28
	global_store_dwordx4 v[36:37], v[20:23], off offset:256
	v_fmac_f32_e32 v40, v29, v29
	s_waitcnt vmcnt(7)
	v_lshlrev_b32_e32 v24, 16, v74
	v_lshlrev_b32_e32 v22, 16, v72
	v_and_b32_e32 v23, 0xffff0000, v72
	v_and_b32_e32 v25, 0xffff0000, v74
	v_lshlrev_b32_e32 v28, 16, v75
	v_and_b32_e32 v29, 0xffff0000, v75
	v_pk_add_f32 v[16:17], v[16:17], v[22:23]
	v_lshlrev_b32_e32 v26, 16, v73
	v_and_b32_e32 v27, 0xffff0000, v73
	v_pk_add_f32 v[22:23], v[14:15], v[28:29]
	v_pk_add_f32 v[14:15], v[12:13], v[24:25]
	v_fma_f32 v24, v16, v16, 0
	v_pk_add_f32 v[18:19], v[18:19], v[26:27]
	v_fmac_f32_e32 v24, v17, v17
	v_fmac_f32_e32 v24, v18, v18
	v_fmac_f32_e32 v24, v19, v19
	v_lshl_add_u64 v[20:21], s[8:9], 0, v[94:95]
	v_fmac_f32_e32 v24, v14, v14
	v_lshl_add_u64 v[20:21], v[20:21], 0, v[156:157]
	v_fmac_f32_e32 v24, v15, v15
	v_cvt_pk_bf16_f32 v12, v16, v17
	v_cvt_pk_bf16_f32 v13, v18, v19
	v_fmac_f32_e32 v24, v22, v22
	v_cvt_pk_bf16_f32 v14, v14, v15
	v_cvt_pk_bf16_f32 v15, v22, v23
	global_store_dwordx4 v[20:21], v[12:15], off
	v_fmac_f32_e32 v24, v23, v23
	s_waitcnt vmcnt(7)
	v_lshlrev_b32_e32 v16, 16, v69
	v_lshlrev_b32_e32 v12, 16, v68
	v_and_b32_e32 v13, 0xffff0000, v68
	v_pk_add_f32 v[8:9], v[8:9], v[12:13]
	v_and_b32_e32 v17, 0xffff0000, v69
	v_fmac_f32_e32 v24, v8, v8
	v_pk_add_f32 v[10:11], v[10:11], v[16:17]
	v_fmac_f32_e32 v24, v9, v9
	v_lshlrev_b32_e32 v14, 16, v70
	v_and_b32_e32 v15, 0xffff0000, v70
	v_lshlrev_b32_e32 v18, 16, v71
	v_and_b32_e32 v19, 0xffff0000, v71
	v_fmac_f32_e32 v24, v10, v10
	v_pk_add_f32 v[12:13], v[6:7], v[18:19]
	v_pk_add_f32 v[6:7], v[4:5], v[14:15]
	v_fmac_f32_e32 v24, v11, v11
	v_fmac_f32_e32 v24, v6, v6
	v_fmac_f32_e32 v24, v7, v7
	v_fmac_f32_e32 v24, v12, v12
	v_cvt_pk_bf16_f32 v4, v8, v9
	v_mov_b32_e32 v8, v40
	v_fmac_f32_e32 v24, v13, v13
	v_cvt_pk_bf16_f32 v5, v10, v11
	v_cvt_pk_bf16_f32 v6, v6, v7
	s_nop 0
	v_permlane16_swap_b32_e32 v40, v8
	v_cvt_pk_bf16_f32 v7, v12, v13
	global_store_dwordx4 v[20:21], v[4:7], off offset:256
	v_add_f32_e32 v10, v40, v8
	v_mov_b32_e32 v8, v24
	v_mov_b32_e32 v4, v60
	v_mov_b32_e32 v6, v44
	s_nop 0
	v_permlane16_swap_b32_e32 v60, v4
	v_permlane16_swap_b32_e32 v44, v6
	v_permlane16_swap_b32_e32 v24, v8
	v_add_f32_e32 v4, v60, v4
	v_add_f32_e32 v6, v44, v6
	v_add_f32_e32 v8, v24, v8
	v_mov_b32_e32 v5, v4
	v_mov_b32_e32 v7, v6
	v_mov_b32_e32 v11, v10
	v_mov_b32_e32 v9, v8
	v_permlane32_swap_b32_e32 v4, v5
	v_permlane32_swap_b32_e32 v6, v7
	v_permlane32_swap_b32_e32 v10, v11
	v_permlane32_swap_b32_e32 v8, v9
	s_and_saveexec_b64 s[0:1], vcc
	s_xor_b64 s[0:1], exec, s[0:1]
	s_cbranch_execz .LBB0_544
	v_cmp_gt_i32_e32 vcc, 3, v183
	s_and_saveexec_b64 s[6:7], vcc
	v_mov_b32_e32 v8, v10
	v_mov_b32_e32 v9, v11
	s_or_b64 exec, exec, s[6:7]

; __device__ __forceinline__ unsigned cvt_pk_bf16(float lo, float hi) { unsigned r; asm volatile("v_cvt_pk_bf16_f32 %0, %1, %2" : "=v"(r) : "v"(lo), "v"(hi)); return r; }
;     __device__ __forceinline__ void operator()(const f32x4 (&acc)[2][2][4][2], const Unit& u, int wr, int wc, int fr, int fq) const {
;     ...
;             for (int m = 0; m < 4; ++m) { const bf16_t* bp = xb + (size_t)(row0 + ai * HALF + m * 16) * ldc + col0;
; #pragma unroll
;                 for (int bj = 0; bj < 2; ++bj) b[m][bj] = *(const u32x4*)(bp + bj * HALF);
;                 sv[m] = ssin ? ssin[row0 + ai * HALF + m * 16] : 0ull; }
; #pragma unroll
;             for (int m = 0; m < 4; ++m) { const int row = row0 + ai * HALF + m * 16; bf16_t* xp = xb + (size_t)row * ldc + col0;
;                 const float sc = ssin ? 1.0f / ((float)sv[m] * (1.f / (16777216.f * 2048.f)) + 1e-6f) : 1.f;
;                 float q = 0.f;
; #pragma unroll
;                 for (int bj = 0; bj < 2; ++bj) { f32x4 v0, v1;
; #pragma unroll
;                     for (int e = 0; e < 2; ++e) { v0[2 * e] = __builtin_bit_cast(float, b[m][bj][e] << 16); v0[2 * e + 1] = __builtin_bit_cast(float, b[m][bj][e] & 0xffff0000u);
;                                                   v1[2 * e] = __builtin_bit_cast(float, b[m][bj][2 + e] << 16); v1[2 * e + 1] = __builtin_bit_cast(float, b[m][bj][2 + e] & 0xffff0000u); }
;                     v0 += acc[ai][bj][m][0] * sc; v1 += acc[ai][bj][m][1] * sc;
;                     q = __builtin_fmaf(v0[0], v0[0], q); q = __builtin_fmaf(v0[1], v0[1], q); q = __builtin_fmaf(v0[2], v0[2], q); q = __builtin_fmaf(v0[3], v0[3], q);
;                     q = __builtin_fmaf(v1[0], v1[0], q); q = __builtin_fmaf(v1[1], v1[1], q); q = __builtin_fmaf(v1[2], v1[2], q); q = __builtin_fmaf(v1[3], v1[3], q);
;                     if (outf) { float* op = outf + (size_t)row * ldc + col0 + bj * HALF; *(f32x4*)op = v0; *(f32x4*)(op + 4) = v1; }
;                     else { u32x4 w; w.x = cvt_pk_bf16(v0[0], v0[1]); w.y = cvt_pk_bf16(v0[2], v0[3]); w.z = cvt_pk_bf16(v1[0], v1[1]); w.w = cvt_pk_bf16(v1[2], v1[3]); *(u32x4*)(xp + bj * HALF) = w; } }
.LBB0_782:
	s_lshl_b32 s46, s46, 8
	s_add_i32 s46, s46, s23
	v_lshl_or_b32 v132, s47, 8, v186
	v_or_b32_e32 v172, s46, v184
	v_ashrrev_i32_e32 v133, 31, v132
	v_lshlrev_b64 v[156:157], 1, v[132:133]
	v_ashrrev_i32_e32 v173, 31, v172
	v_lshl_add_u64 v[158:159], s[8:9], 0, v[156:157]
	v_lshlrev_b64 v[194:195], 12, v[172:173]
	v_lshl_add_u64 v[132:133], v[158:159], 0, v[194:195]
	global_load_dwordx4 v[168:171], v[132:133], off
	global_load_dwordx4 v[190:193], v[132:133], off offset:256
	v_or_b32_e32 v132, 16, v172
	v_ashrrev_i32_e32 v133, 31, v132
	v_lshlrev_b64 v[178:179], 12, v[132:133]
	v_lshl_add_u64 v[132:133], v[158:159], 0, v[178:179]
	global_load_dwordx4 v[152:155], v[132:133], off
	global_load_dwordx4 v[148:151], v[132:133], off offset:256
	v_or_b32_e32 v132, 32, v172
	v_ashrrev_i32_e32 v133, 31, v132
	v_lshlrev_b64 v[176:177], 12, v[132:133]
	v_lshl_add_u64 v[132:133], v[158:159], 0, v[176:177]
	global_load_dwordx4 v[144:147], v[132:133], off
	global_load_dwordx4 v[140:143], v[132:133], off offset:256
	v_or_b32_e32 v132, 48, v172
	v_ashrrev_i32_e32 v133, 31, v132
	v_lshlrev_b64 v[174:175], 12, v[132:133]
	v_lshl_add_u64 v[132:133], v[158:159], 0, v[174:175]
	global_load_dwordx4 v[136:139], v[132:133], off
	s_nop 0
	global_load_dwordx4 v[132:135], v[132:133], off offset:256
	v_lshlrev_b64 v[208:209], 12, v[172:173]
	v_lshl_add_u64 v[208:209], v[158:159], 0, v[208:209]
	v_mov_b32_e32 v212, 0x10000
	v_mov_b32_e32 v213, 0
	v_mov_b32_e32 v214, 0x80000
	v_mov_b32_e32 v215, 0
	v_lshl_add_u64 v[210:211], v[208:209], 0, v[214:215]
	global_load_dwordx4 v[218:221], v[210:211], off
	global_load_dwordx4 v[222:225], v[210:211], off offset:256
	v_lshl_add_u64 v[210:211], v[210:211], 0, v[212:213]
	global_load_dwordx4 v[226:229], v[210:211], off
	global_load_dwordx4 v[230:233], v[210:211], off offset:256
	v_lshl_add_u64 v[210:211], v[210:211], 0, v[212:213]
	global_load_dwordx4 v[234:237], v[210:211], off
	global_load_dwordx4 v[238:241], v[210:211], off offset:256
	v_lshl_add_u64 v[210:211], v[210:211], 0, v[212:213]
	global_load_dwordx4 v[242:245], v[210:211], off
	global_load_dwordx4 v[246:249], v[210:211], off offset:256
	v_lshl_add_u64 v[194:195], s[8:9], 0, v[194:195]
	v_lshl_add_u64 v[194:195], v[194:195], 0, v[156:157]
	v_cmp_lt_i32_e32 vcc, 1, v183
	s_waitcnt vmcnt(15)
	v_lshlrev_b32_e32 v196, 16, v168
	v_and_b32_e32 v197, 0xffff0000, v168
	v_lshlrev_b32_e32 v198, 16, v170
	v_and_b32_e32 v199, 0xffff0000, v170
	v_lshlrev_b32_e32 v168, 16, v169
	v_and_b32_e32 v169, 0xffff0000, v169
	v_lshlrev_b32_e32 v170, 16, v171
	v_and_b32_e32 v171, 0xffff0000, v171
	v_pk_add_f32 v[128:129], v[128:129], v[196:197]
	v_pk_add_f32 v[130:131], v[130:131], v[168:169]
	v_pk_add_f32 v[168:169], v[126:127], v[170:171]
	v_pk_add_f32 v[170:171], v[124:125], v[198:199]
	v_fma_f32 v124, v128, v128, 0
	v_fmac_f32_e32 v124, v129, v129
	v_fmac_f32_e32 v124, v130, v130
	v_fmac_f32_e32 v124, v131, v131
	v_fmac_f32_e32 v124, v170, v170
	v_fmac_f32_e32 v124, v171, v171
	v_cvt_pk_bf16_f32 v126, v128, v129
	v_cvt_pk_bf16_f32 v127, v130, v131
	v_fmac_f32_e32 v124, v168, v168
	v_cvt_pk_bf16_f32 v128, v170, v171
	v_cvt_pk_bf16_f32 v129, v168, v169
	global_store_dwordx4 v[194:195], v[126:129], off
	v_fmac_f32_e32 v124, v169, v169
	s_waitcnt vmcnt(15)
	v_lshlrev_b32_e32 v130, 16, v191
	v_lshlrev_b32_e32 v126, 16, v190
	v_and_b32_e32 v127, 0xffff0000, v190
	v_pk_add_f32 v[120:121], v[120:121], v[126:127]
	v_and_b32_e32 v131, 0xffff0000, v191
	v_fmac_f32_e32 v124, v120, v120
	v_pk_add_f32 v[122:123], v[122:123], v[130:131]
	v_fmac_f32_e32 v124, v121, v121
	v_lshlrev_b32_e32 v128, 16, v192
	v_and_b32_e32 v129, 0xffff0000, v192
	v_lshlrev_b32_e32 v168, 16, v193
	v_and_b32_e32 v169, 0xffff0000, v193
	v_fmac_f32_e32 v124, v122, v122
	v_pk_add_f32 v[126:127], v[118:119], v[168:169]
	v_pk_add_f32 v[118:119], v[116:117], v[128:129]
	v_fmac_f32_e32 v124, v123, v123
	v_fmac_f32_e32 v124, v118, v118
	v_fmac_f32_e32 v124, v119, v119
	v_cvt_pk_bf16_f32 v116, v120, v121
	v_cvt_pk_bf16_f32 v117, v122, v123
	v_cvt_pk_bf16_f32 v118, v118, v119
	v_cvt_pk_bf16_f32 v119, v126, v127
	v_fmac_f32_e32 v124, v126, v126
	global_store_dwordx4 v[194:195], v[116:119], off offset:256
	v_fmac_f32_e32 v124, v127, v127
	s_waitcnt vmcnt(15)
	v_lshlrev_b32_e32 v120, 16, v154
	v_lshlrev_b32_e32 v118, 16, v152
	v_and_b32_e32 v119, 0xffff0000, v152
	v_and_b32_e32 v121, 0xffff0000, v154
	v_lshlrev_b32_e32 v126, 16, v155
	v_and_b32_e32 v127, 0xffff0000, v155
	v_pk_add_f32 v[112:113], v[112:113], v[118:119]
	v_lshlrev_b32_e32 v122, 16, v153
	v_and_b32_e32 v123, 0xffff0000, v153
	v_pk_add_f32 v[118:119], v[110:111], v[126:127]
	v_pk_add_f32 v[110:111], v[108:109], v[120:121]
	v_fma_f32 v120, v112, v112, 0
	v_pk_add_f32 v[114:115], v[114:115], v[122:123]
	v_fmac_f32_e32 v120, v113, v113
	v_fmac_f32_e32 v120, v114, v114
	v_fmac_f32_e32 v120, v115, v115
	v_lshl_add_u64 v[116:117], s[8:9], 0, v[178:179]
	v_fmac_f32_e32 v120, v110, v110
	v_lshl_add_u64 v[116:117], v[116:117], 0, v[156:157]
	v_fmac_f32_e32 v120, v111, v111
	v_cvt_pk_bf16_f32 v108, v112, v113
	v_cvt_pk_bf16_f32 v109, v114, v115
	v_fmac_f32_e32 v120, v118, v118
	v_cvt_pk_bf16_f32 v110, v110, v111
	v_cvt_pk_bf16_f32 v111, v118, v119
	global_store_dwordx4 v[116:117], v[108:111], off
	v_fmac_f32_e32 v120, v119, v119
	s_waitcnt vmcnt(15)
; __device__ __forceinline__ unsigned cvt_pk_bf16(float lo, float hi) { unsigned r; asm volatile("v_cvt_pk_bf16_f32 %0, %1, %2" : "=v"(r) : "v"(lo), "v"(hi)); return r; }
;     __device__ __forceinline__ void operator()(const f32x4 (&acc)[2][2][4][2], const Unit& u, int wr, int wc, int fr, int fq) const {
;     ...
;             for (int m = 0; m < 4; ++m) { const int row = row0 + ai * HALF + m * 16; bf16_t* xp = xb + (size_t)row * ldc + col0;
;                 const float sc = ssin ? 1.0f / ((float)sv[m] * (1.f / (16777216.f * 2048.f)) + 1e-6f) : 1.f;
;                 float q = 0.f;
; #pragma unroll
;                 for (int bj = 0; bj < 2; ++bj) { f32x4 v0, v1;
; #pragma unroll
;                     for (int e = 0; e < 2; ++e) { v0[2 * e] = __builtin_bit_cast(float, b[m][bj][e] << 16); v0[2 * e + 1] = __builtin_bit_cast(float, b[m][bj][e] & 0xffff0000u);
;                                                   v1[2 * e] = __builtin_bit_cast(float, b[m][bj][2 + e] << 16); v1[2 * e + 1] = __builtin_bit_cast(float, b[m][bj][2 + e] & 0xffff0000u); }
;                     v0 += acc[ai][bj][m][0] * sc; v1 += acc[ai][bj][m][1] * sc;
;                     q = __builtin_fmaf(v0[0], v0[0], q); q = __builtin_fmaf(v0[1], v0[1], q); q = __builtin_fmaf(v0[2], v0[2], q); q = __builtin_fmaf(v0[3], v0[3], q);
;                     q = __builtin_fmaf(v1[0], v1[0], q); q = __builtin_fmaf(v1[1], v1[1], q); q = __builtin_fmaf(v1[2], v1[2], q); q = __builtin_fmaf(v1[3], v1[3], q);
;                     if (outf) { float* op = outf + (size_t)row * ldc + col0 + bj * HALF; *(f32x4*)op = v0; *(f32x4*)(op + 4) = v1; }
;                     else { u32x4 w; w.x = cvt_pk_bf16(v0[0], v0[1]); w.y = cvt_pk_bf16(v0[2], v0[3]); w.z = cvt_pk_bf16(v1[0], v1[1]); w.w = cvt_pk_bf16(v1[2], v1[3]); *(u32x4*)(xp + bj * HALF) = w; } }
;                 sq[ai][m] = q; }
;             asm volatile("" ::: "memory");
; #pragma unroll
;             for (int m = 0; m < 4; ++m) { float q = sq[ai][m]; q = fq_sum(q); sq[ai][m] = q; }
;             const float v = fq == 0 ? sq[ai][0] : (fq == 1 ? sq[ai][1] : (fq == 2 ? sq[ai][2] : sq[ai][3]));
	v_lshlrev_b32_e32 v112, 16, v149
	v_lshlrev_b32_e32 v108, 16, v148
	v_and_b32_e32 v109, 0xffff0000, v148
	v_pk_add_f32 v[104:105], v[104:105], v[108:109]
	v_and_b32_e32 v113, 0xffff0000, v149
	v_fmac_f32_e32 v120, v104, v104
	v_pk_add_f32 v[106:107], v[106:107], v[112:113]
	v_fmac_f32_e32 v120, v105, v105
	v_lshlrev_b32_e32 v110, 16, v150
	v_and_b32_e32 v111, 0xffff0000, v150
	v_lshlrev_b32_e32 v114, 16, v151
	v_and_b32_e32 v115, 0xffff0000, v151
	v_fmac_f32_e32 v120, v106, v106
	v_pk_add_f32 v[108:109], v[102:103], v[114:115]
	v_pk_add_f32 v[102:103], v[100:101], v[110:111]
	v_fmac_f32_e32 v120, v107, v107
	v_fmac_f32_e32 v120, v102, v102
	v_fmac_f32_e32 v120, v103, v103
	v_cvt_pk_bf16_f32 v100, v104, v105
	v_cvt_pk_bf16_f32 v101, v106, v107
	v_cvt_pk_bf16_f32 v102, v102, v103
	v_cvt_pk_bf16_f32 v103, v108, v109
	v_fmac_f32_e32 v120, v108, v108
	global_store_dwordx4 v[116:117], v[100:103], off offset:256
	v_fmac_f32_e32 v120, v109, v109
	s_waitcnt vmcnt(15)
	v_lshlrev_b32_e32 v104, 16, v146
	v_lshlrev_b32_e32 v102, 16, v144
	v_and_b32_e32 v103, 0xffff0000, v144
	v_and_b32_e32 v105, 0xffff0000, v146
	v_lshlrev_b32_e32 v108, 16, v147
	v_and_b32_e32 v109, 0xffff0000, v147
	v_pk_add_f32 v[96:97], v[96:97], v[102:103]
	v_lshlrev_b32_e32 v106, 16, v145
	v_and_b32_e32 v107, 0xffff0000, v145
	v_pk_add_f32 v[102:103], v[94:95], v[108:109]
	v_pk_add_f32 v[94:95], v[92:93], v[104:105]
	v_fma_f32 v104, v96, v96, 0
	v_pk_add_f32 v[98:99], v[98:99], v[106:107]
	v_fmac_f32_e32 v104, v97, v97
	v_fmac_f32_e32 v104, v98, v98
	v_fmac_f32_e32 v104, v99, v99
	v_lshl_add_u64 v[100:101], s[8:9], 0, v[176:177]
	v_fmac_f32_e32 v104, v94, v94
	v_lshl_add_u64 v[100:101], v[100:101], 0, v[156:157]
	v_fmac_f32_e32 v104, v95, v95
	v_cvt_pk_bf16_f32 v92, v96, v97
	v_cvt_pk_bf16_f32 v93, v98, v99
	v_fmac_f32_e32 v104, v102, v102
	v_cvt_pk_bf16_f32 v94, v94, v95
	v_cvt_pk_bf16_f32 v95, v102, v103
	global_store_dwordx4 v[100:101], v[92:95], off
	v_fmac_f32_e32 v104, v103, v103
	s_waitcnt vmcnt(15)
	v_lshlrev_b32_e32 v96, 16, v141
	v_lshlrev_b32_e32 v92, 16, v140
	v_and_b32_e32 v93, 0xffff0000, v140
	v_pk_add_f32 v[88:89], v[88:89], v[92:93]
	v_and_b32_e32 v97, 0xffff0000, v141
	v_fmac_f32_e32 v104, v88, v88
	v_pk_add_f32 v[90:91], v[90:91], v[96:97]
	v_fmac_f32_e32 v104, v89, v89
	v_lshlrev_b32_e32 v94, 16, v142
	v_and_b32_e32 v95, 0xffff0000, v142
	v_lshlrev_b32_e32 v98, 16, v143
	v_and_b32_e32 v99, 0xffff0000, v143
	v_fmac_f32_e32 v104, v90, v90
	v_pk_add_f32 v[92:93], v[86:87], v[98:99]
	v_pk_add_f32 v[86:87], v[84:85], v[94:95]
	v_fmac_f32_e32 v104, v91, v91
	v_fmac_f32_e32 v104, v86, v86
	v_fmac_f32_e32 v104, v87, v87
	v_cvt_pk_bf16_f32 v84, v88, v89
	v_cvt_pk_bf16_f32 v85, v90, v91
	v_cvt_pk_bf16_f32 v86, v86, v87
	v_cvt_pk_bf16_f32 v87, v92, v93
	v_fmac_f32_e32 v104, v92, v92
	global_store_dwordx4 v[100:101], v[84:87], off offset:256
	v_fmac_f32_e32 v104, v93, v93
	s_waitcnt vmcnt(15)
	v_lshlrev_b32_e32 v88, 16, v138
	v_lshlrev_b32_e32 v86, 16, v136
	v_and_b32_e32 v87, 0xffff0000, v136
	v_and_b32_e32 v89, 0xffff0000, v138
	v_lshlrev_b32_e32 v92, 16, v139
	v_and_b32_e32 v93, 0xffff0000, v139
	v_pk_add_f32 v[80:81], v[80:81], v[86:87]
	v_lshlrev_b32_e32 v90, 16, v137
	v_and_b32_e32 v91, 0xffff0000, v137
	v_pk_add_f32 v[86:87], v[78:79], v[92:93]
	v_pk_add_f32 v[78:79], v[76:77], v[88:89]
	v_fma_f32 v88, v80, v80, 0
	v_pk_add_f32 v[82:83], v[82:83], v[90:91]
	v_fmac_f32_e32 v88, v81, v81
	v_fmac_f32_e32 v88, v82, v82
	v_fmac_f32_e32 v88, v83, v83
	v_lshl_add_u64 v[84:85], s[8:9], 0, v[174:175]
	v_fmac_f32_e32 v88, v78, v78
	v_lshl_add_u64 v[84:85], v[84:85], 0, v[156:157]
	v_fmac_f32_e32 v88, v79, v79
	v_cvt_pk_bf16_f32 v76, v80, v81
	v_cvt_pk_bf16_f32 v77, v82, v83
	v_fmac_f32_e32 v88, v86, v86
	v_cvt_pk_bf16_f32 v78, v78, v79
	v_cvt_pk_bf16_f32 v79, v86, v87
	global_store_dwordx4 v[84:85], v[76:79], off
	v_fmac_f32_e32 v88, v87, v87
	s_waitcnt vmcnt(15)
	v_lshlrev_b32_e32 v80, 16, v133
	v_lshlrev_b32_e32 v76, 16, v132
	v_and_b32_e32 v77, 0xffff0000, v132
	v_pk_add_f32 v[72:73], v[72:73], v[76:77]
	v_and_b32_e32 v81, 0xffff0000, v133
	v_fmac_f32_e32 v88, v72, v72
	v_pk_add_f32 v[74:75], v[74:75], v[80:81]
	v_fmac_f32_e32 v88, v73, v73
	v_lshlrev_b32_e32 v78, 16, v134
	v_and_b32_e32 v79, 0xffff0000, v134
	v_lshlrev_b32_e32 v82, 16, v135
	v_and_b32_e32 v83, 0xffff0000, v135
	v_fmac_f32_e32 v88, v74, v74
	v_pk_add_f32 v[76:77], v[70:71], v[82:83]
	v_pk_add_f32 v[70:71], v[68:69], v[78:79]
	v_fmac_f32_e32 v88, v75, v75
	v_fmac_f32_e32 v88, v70, v70
	v_cvt_pk_bf16_f32 v68, v72, v73
	v_fmac_f32_e32 v88, v71, v71
	v_cvt_pk_bf16_f32 v69, v74, v75
	v_cvt_pk_bf16_f32 v70, v70, v71
	v_cvt_pk_bf16_f32 v71, v76, v77
	global_store_dwordx4 v[84:85], v[68:71], off offset:256
	v_fmac_f32_e32 v88, v76, v76
	v_fmac_f32_e32 v88, v77, v77
	v_mov_b32_e32 v68, v124
	s_nop 1
	v_permlane16_swap_b32_e32 v124, v68
	v_add_f32_e32 v70, v124, v68
	v_mov_b32_e32 v68, v120
	s_nop 1
	v_permlane16_swap_b32_e32 v120, v68
	v_add_f32_e32 v72, v120, v68
	v_mov_b32_e32 v68, v104
	s_nop 1
	v_permlane16_swap_b32_e32 v104, v68
	v_add_f32_e32 v74, v104, v68
	v_mov_b32_e32 v68, v88
	s_nop 1
	v_permlane16_swap_b32_e32 v88, v68
	v_add_f32_e32 v68, v88, v68
	v_mov_b32_e32 v71, v70
	v_mov_b32_e32 v73, v72
	v_mov_b32_e32 v75, v74
	v_mov_b32_e32 v69, v68
	v_permlane32_swap_b32_e32 v70, v71
	v_permlane32_swap_b32_e32 v72, v73
	v_permlane32_swap_b32_e32 v74, v75
	v_permlane32_swap_b32_e32 v68, v69
	s_and_saveexec_b64 s[0:1], vcc
	s_xor_b64 s[0:1], exec, s[0:1]
	s_cbranch_execz .LBB0_788
	v_cmp_lt_i32_e32 vcc, 2, v183
	s_and_saveexec_b64 s[6:7], vcc
	s_xor_b64 s[6:7], exec, s[6:7]
	s_andn2_saveexec_b64 s[6:7], s[6:7]
	v_mov_b32_e32 v68, v74
	v_mov_b32_e32 v69, v75
	s_or_b64 exec, exec, s[6:7]

;     __device__ __forceinline__ void operator()(const f32x4 (&acc)[2][2][4][2], const Unit& u, int wr, int wc, int fr, int fq) const {
;     ...
;             for (int m = 0; m < 4; ++m) { const bf16_t* bp = xb + (size_t)(row0 + ai * HALF + m * 16) * ldc + col0;
; #pragma unroll
;                 for (int bj = 0; bj < 2; ++bj) b[m][bj] = *(const u32x4*)(bp + bj * HALF);
;                 sv[m] = ssin ? ssin[row0 + ai * HALF + m * 16] : 0ull; }
; #pragma unroll
;             for (int m = 0; m < 4; ++m) { const int row = row0 + ai * HALF + m * 16; bf16_t* xp = xb + (size_t)row * ldc + col0;
;                 const float sc = ssin ? 1.0f / ((float)sv[m] * (1.f / (16777216.f * 2048.f)) + 1e-6f) : 1.f;
;                 float q = 0.f;
; #pragma unroll
;                 for (int bj = 0; bj < 2; ++bj) { f32x4 v0, v1;
; #pragma unroll
;                     for (int e = 0; e < 2; ++e) { v0[2 * e] = __builtin_bit_cast(float, b[m][bj][e] << 16); v0[2 * e + 1] = __builtin_bit_cast(float, b[m][bj][e] & 0xffff0000u);
;                                                   v1[2 * e] = __builtin_bit_cast(float, b[m][bj][2 + e] << 16); v1[2 * e + 1] = __builtin_bit_cast(float, b[m][bj][2 + e] & 0xffff0000u); }
;                     v0 += acc[ai][bj][m][0] * sc; v1 += acc[ai][bj][m][1] * sc;
;                     q = __builtin_fmaf(v0[0], v0[0], q); q = __builtin_fmaf(v0[1], v0[1], q); q = __builtin_fmaf(v0[2], v0[2], q); q = __builtin_fmaf(v0[3], v0[3], q);
;                     q = __builtin_fmaf(v1[0], v1[0], q); q = __builtin_fmaf(v1[1], v1[1], q); q = __builtin_fmaf(v1[2], v1[2], q); q = __builtin_fmaf(v1[3], v1[3], q);
;                     if (outf) { float* op = outf + (size_t)row * ldc + col0 + bj * HALF; *(f32x4*)op = v0; *(f32x4*)(op + 4) = v1; }
;                     else { u32x4 w; w.x = cvt_pk_bf16(v0[0], v0[1]); w.y = cvt_pk_bf16(v0[2], v0[3]); w.z = cvt_pk_bf16(v1[0], v1[1]); w.w = cvt_pk_bf16(v1[2], v1[3]); *(u32x4*)(xp + bj * HALF) = w; } }
;                 sq[ai][m] = q; }
;             asm volatile("" ::: "memory");
; #pragma unroll
;             for (int m = 0; m < 4; ++m) { float q = sq[ai][m]; q = fq_sum(q); sq[ai][m] = q; }
;             const float v = fq == 0 ? sq[ai][0] : (fq == 1 ? sq[ai][1] : (fq == 2 ? sq[ai][2] : sq[ai][3]));
;             atomicAdd(ssout + (u.pm * BM + wr * 64 + ai * HALF + fq * 16 + fr), (unsigned long long)(v * 16777216.f));
.LBB0_792:
	s_or_b64 exec, exec, s[0:1]
	v_add_f32_e32 v70, v68, v69
	v_mul_f32_e32 v70, 0x4b800000, v70
	v_trunc_f32_e32 v70, v70
	v_mul_f32_e32 v71, 0x2f800000, v70
	v_floor_f32_e32 v71, v71
	v_fmac_f32_e32 v70, 0xcf800000, v71
	v_cvt_u32_f32_e32 v70, v70
	v_cvt_u32_f32_e32 v71, v71
	v_or_b32_e32 v92, s46, v185
	v_ashrrev_i32_e32 v93, 31, v92
	v_lshl_add_u64 v[68:69], v[92:93], 3, s[10:11]
	global_atomic_add_x2 v[68:69], v[70:71], off
	v_lshlrev_b64 v[68:69], 12, v[172:173]
	s_mov_b64 s[0:1], 0x80000
	v_lshl_add_u64 v[108:109], v[68:69], 0, s[0:1]
	v_lshl_add_u64 v[70:71], v[158:159], 0, v[108:109]
	s_waitcnt vmcnt(8)
	v_mov_b64_e32 v[100:101], v[218:219]
	v_mov_b64_e32 v[102:103], v[220:221]
	v_mov_b64_e32 v[104:105], v[222:223]
	v_mov_b64_e32 v[106:107], v[224:225]
	s_mov_b64 s[0:1], 0x90000
	v_lshl_add_u64 v[98:99], v[68:69], 0, s[0:1]
	v_lshl_add_u64 v[70:71], v[158:159], 0, v[98:99]
	v_mov_b64_e32 v[88:89], v[226:227]
	v_mov_b64_e32 v[90:91], v[228:229]
	v_mov_b64_e32 v[84:85], v[230:231]
	v_mov_b64_e32 v[86:87], v[232:233]
	s_mov_b64 s[0:1], 0xa0000
	v_lshl_add_u64 v[96:97], v[68:69], 0, s[0:1]
	v_lshl_add_u64 v[70:71], v[158:159], 0, v[96:97]
	v_mov_b64_e32 v[80:81], v[234:235]
	v_mov_b64_e32 v[82:83], v[236:237]
	v_mov_b64_e32 v[76:77], v[238:239]
	v_mov_b64_e32 v[78:79], v[240:241]
	s_mov_b64 s[0:1], 0xb0000
	v_lshl_add_u64 v[94:95], v[68:69], 0, s[0:1]
	v_lshl_add_u64 v[68:69], v[158:159], 0, v[94:95]
	v_mov_b64_e32 v[72:73], v[242:243]
	v_mov_b64_e32 v[74:75], v[244:245]
	s_nop 0
	v_mov_b64_e32 v[68:69], v[246:247]
	v_mov_b64_e32 v[70:71], v[248:249]
	v_lshl_add_u64 v[108:109], s[8:9], 0, v[108:109]
	v_lshl_add_u64 v[108:109], v[108:109], 0, v[156:157]
	v_cmp_lt_i32_e32 vcc, 1, v183
	s_waitcnt vmcnt(7)
	v_lshlrev_b32_e32 v110, 16, v100
	v_and_b32_e32 v111, 0xffff0000, v100
	v_lshlrev_b32_e32 v112, 16, v102
	v_and_b32_e32 v113, 0xffff0000, v102
	v_lshlrev_b32_e32 v100, 16, v101
	v_and_b32_e32 v101, 0xffff0000, v101
	v_lshlrev_b32_e32 v102, 16, v103
	v_and_b32_e32 v103, 0xffff0000, v103
	v_pk_add_f32 v[64:65], v[64:65], v[110:111]
	v_pk_add_f32 v[66:67], v[66:67], v[100:101]
	v_pk_add_f32 v[100:101], v[62:63], v[102:103]
	v_pk_add_f32 v[102:103], v[60:61], v[112:113]
	v_fma_f32 v60, v64, v64, 0
	v_fmac_f32_e32 v60, v65, v65
	v_fmac_f32_e32 v60, v66, v66
	v_fmac_f32_e32 v60, v67, v67
	v_fmac_f32_e32 v60, v102, v102
	v_fmac_f32_e32 v60, v103, v103
	v_cvt_pk_bf16_f32 v62, v64, v65
	v_cvt_pk_bf16_f32 v63, v66, v67
	v_fmac_f32_e32 v60, v100, v100
	v_cvt_pk_bf16_f32 v64, v102, v103
	v_cvt_pk_bf16_f32 v65, v100, v101
	global_store_dwordx4 v[108:109], v[62:65], off
	v_fmac_f32_e32 v60, v101, v101
	s_waitcnt vmcnt(7)
	v_lshlrev_b32_e32 v66, 16, v105
	v_lshlrev_b32_e32 v62, 16, v104
	v_and_b32_e32 v63, 0xffff0000, v104
	v_pk_add_f32 v[56:57], v[56:57], v[62:63]
	v_and_b32_e32 v67, 0xffff0000, v105
	v_fmac_f32_e32 v60, v56, v56
	v_pk_add_f32 v[58:59], v[58:59], v[66:67]
	v_fmac_f32_e32 v60, v57, v57
	v_lshlrev_b32_e32 v64, 16, v106
	v_and_b32_e32 v65, 0xffff0000, v106
	v_lshlrev_b32_e32 v100, 16, v107
	v_and_b32_e32 v101, 0xffff0000, v107
	v_fmac_f32_e32 v60, v58, v58
	v_pk_add_f32 v[62:63], v[54:55], v[100:101]
	v_pk_add_f32 v[54:55], v[52:53], v[64:65]
	v_fmac_f32_e32 v60, v59, v59
	v_fmac_f32_e32 v60, v54, v54
	v_fmac_f32_e32 v60, v55, v55
	v_cvt_pk_bf16_f32 v52, v56, v57
	v_cvt_pk_bf16_f32 v53, v58, v59
	v_cvt_pk_bf16_f32 v54, v54, v55
	v_cvt_pk_bf16_f32 v55, v62, v63
	global_store_dwordx4 v[108:109], v[52:55], off offset:256
	s_waitcnt vmcnt(7)
	v_lshlrev_b32_e32 v56, 16, v90
	v_and_b32_e32 v57, 0xffff0000, v90
	v_lshlrev_b32_e32 v54, 16, v88
	v_and_b32_e32 v55, 0xffff0000, v88
	v_pk_add_f32 v[48:49], v[48:49], v[54:55]
	v_lshlrev_b32_e32 v58, 16, v89
	v_and_b32_e32 v59, 0xffff0000, v89
	v_pk_add_f32 v[56:57], v[44:45], v[56:57]
	v_fma_f32 v44, v48, v48, 0
	v_pk_add_f32 v[50:51], v[50:51], v[58:59]
	v_fmac_f32_e32 v44, v49, v49
	v_fmac_f32_e32 v44, v50, v50
	v_fmac_f32_e32 v60, v62, v62
	v_fmac_f32_e32 v44, v51, v51
	v_fmac_f32_e32 v60, v63, v63
	v_lshl_add_u64 v[52:53], s[8:9], 0, v[98:99]
	v_lshlrev_b32_e32 v62, 16, v91
	v_and_b32_e32 v63, 0xffff0000, v91
	v_fmac_f32_e32 v44, v56, v56
	v_lshl_add_u64 v[52:53], v[52:53], 0, v[156:157]
	v_pk_add_f32 v[54:55], v[46:47], v[62:63]
	v_fmac_f32_e32 v44, v57, v57
	v_cvt_pk_bf16_f32 v46, v48, v49
	v_cvt_pk_bf16_f32 v47, v50, v51
	v_fmac_f32_e32 v44, v54, v54
	v_cvt_pk_bf16_f32 v48, v56, v57
	v_cvt_pk_bf16_f32 v49, v54, v55
	global_store_dwordx4 v[52:53], v[46:49], off
	v_fmac_f32_e32 v44, v55, v55
	s_waitcnt vmcnt(7)
; __device__ __forceinline__ unsigned cvt_pk_bf16(float lo, float hi) { unsigned r; asm volatile("v_cvt_pk_bf16_f32 %0, %1, %2" : "=v"(r) : "v"(lo), "v"(hi)); return r; }
;     __device__ __forceinline__ void operator()(const f32x4 (&acc)[2][2][4][2], const Unit& u, int wr, int wc, int fr, int fq) const {
;     ...
;             for (int m = 0; m < 4; ++m) { const int row = row0 + ai * HALF + m * 16; bf16_t* xp = xb + (size_t)row * ldc + col0;
;                 const float sc = ssin ? 1.0f / ((float)sv[m] * (1.f / (16777216.f * 2048.f)) + 1e-6f) : 1.f;
;                 float q = 0.f;
; #pragma unroll
;                 for (int bj = 0; bj < 2; ++bj) { f32x4 v0, v1;
; #pragma unroll
;                     for (int e = 0; e < 2; ++e) { v0[2 * e] = __builtin_bit_cast(float, b[m][bj][e] << 16); v0[2 * e + 1] = __builtin_bit_cast(float, b[m][bj][e] & 0xffff0000u);
;                                                   v1[2 * e] = __builtin_bit_cast(float, b[m][bj][2 + e] << 16); v1[2 * e + 1] = __builtin_bit_cast(float, b[m][bj][2 + e] & 0xffff0000u); }
;                     v0 += acc[ai][bj][m][0] * sc; v1 += acc[ai][bj][m][1] * sc;
;                     q = __builtin_fmaf(v0[0], v0[0], q); q = __builtin_fmaf(v0[1], v0[1], q); q = __builtin_fmaf(v0[2], v0[2], q); q = __builtin_fmaf(v0[3], v0[3], q);
;                     q = __builtin_fmaf(v1[0], v1[0], q); q = __builtin_fmaf(v1[1], v1[1], q); q = __builtin_fmaf(v1[2], v1[2], q); q = __builtin_fmaf(v1[3], v1[3], q);
;                     if (outf) { float* op = outf + (size_t)row * ldc + col0 + bj * HALF; *(f32x4*)op = v0; *(f32x4*)(op + 4) = v1; }
;                     else { u32x4 w; w.x = cvt_pk_bf16(v0[0], v0[1]); w.y = cvt_pk_bf16(v0[2], v0[3]); w.z = cvt_pk_bf16(v1[0], v1[1]); w.w = cvt_pk_bf16(v1[2], v1[3]); *(u32x4*)(xp + bj * HALF) = w; } }
;                 sq[ai][m] = q; }
;             asm volatile("" ::: "memory");
; #pragma unroll
;             for (int m = 0; m < 4; ++m) { float q = sq[ai][m]; q = fq_sum(q); sq[ai][m] = q; }
;             const float v = fq == 0 ? sq[ai][0] : (fq == 1 ? sq[ai][1] : (fq == 2 ? sq[ai][2] : sq[ai][3]));
	v_lshlrev_b32_e32 v50, 16, v85
	v_lshlrev_b32_e32 v46, 16, v84
	v_and_b32_e32 v47, 0xffff0000, v84
	v_pk_add_f32 v[40:41], v[40:41], v[46:47]
	v_and_b32_e32 v51, 0xffff0000, v85
	v_fmac_f32_e32 v44, v40, v40
	v_pk_add_f32 v[42:43], v[42:43], v[50:51]
	v_fmac_f32_e32 v44, v41, v41
	v_lshlrev_b32_e32 v48, 16, v86
	v_and_b32_e32 v49, 0xffff0000, v86
	v_lshlrev_b32_e32 v54, 16, v87
	v_and_b32_e32 v55, 0xffff0000, v87
	v_fmac_f32_e32 v44, v42, v42
	v_pk_add_f32 v[46:47], v[38:39], v[54:55]
	v_pk_add_f32 v[38:39], v[36:37], v[48:49]
	v_fmac_f32_e32 v44, v43, v43
	v_fmac_f32_e32 v44, v38, v38
	v_fmac_f32_e32 v44, v39, v39
	v_cvt_pk_bf16_f32 v36, v40, v41
	v_cvt_pk_bf16_f32 v37, v42, v43
	v_cvt_pk_bf16_f32 v38, v38, v39
	v_cvt_pk_bf16_f32 v39, v46, v47
	v_fmac_f32_e32 v44, v46, v46
	global_store_dwordx4 v[52:53], v[36:39], off offset:256
	v_fmac_f32_e32 v44, v47, v47
	s_waitcnt vmcnt(7)
	v_lshlrev_b32_e32 v40, 16, v82
	v_lshlrev_b32_e32 v38, 16, v80
	v_and_b32_e32 v39, 0xffff0000, v80
	v_and_b32_e32 v41, 0xffff0000, v82
	v_lshlrev_b32_e32 v46, 16, v83
	v_and_b32_e32 v47, 0xffff0000, v83
	v_pk_add_f32 v[32:33], v[32:33], v[38:39]
	v_lshlrev_b32_e32 v42, 16, v81
	v_and_b32_e32 v43, 0xffff0000, v81
	v_pk_add_f32 v[38:39], v[30:31], v[46:47]
	v_pk_add_f32 v[30:31], v[28:29], v[40:41]
	v_fma_f32 v40, v32, v32, 0
	v_pk_add_f32 v[34:35], v[34:35], v[42:43]
	v_fmac_f32_e32 v40, v33, v33
	v_fmac_f32_e32 v40, v34, v34
	v_fmac_f32_e32 v40, v35, v35
	v_lshl_add_u64 v[36:37], s[8:9], 0, v[96:97]
	v_fmac_f32_e32 v40, v30, v30
	v_lshl_add_u64 v[36:37], v[36:37], 0, v[156:157]
	v_fmac_f32_e32 v40, v31, v31
	v_cvt_pk_bf16_f32 v28, v32, v33
	v_cvt_pk_bf16_f32 v29, v34, v35
	v_fmac_f32_e32 v40, v38, v38
	v_cvt_pk_bf16_f32 v30, v30, v31
	v_cvt_pk_bf16_f32 v31, v38, v39
	global_store_dwordx4 v[36:37], v[28:31], off
	v_fmac_f32_e32 v40, v39, v39
	s_waitcnt vmcnt(7)
	v_lshlrev_b32_e32 v32, 16, v77
	v_lshlrev_b32_e32 v28, 16, v76
	v_and_b32_e32 v29, 0xffff0000, v76
	v_pk_add_f32 v[24:25], v[24:25], v[28:29]
	v_and_b32_e32 v33, 0xffff0000, v77
	v_fmac_f32_e32 v40, v24, v24
	v_pk_add_f32 v[26:27], v[26:27], v[32:33]
	v_fmac_f32_e32 v40, v25, v25
	v_lshlrev_b32_e32 v30, 16, v78
	v_and_b32_e32 v31, 0xffff0000, v78
	v_lshlrev_b32_e32 v34, 16, v79
	v_and_b32_e32 v35, 0xffff0000, v79
	v_fmac_f32_e32 v40, v26, v26
	v_pk_add_f32 v[28:29], v[22:23], v[34:35]
	v_pk_add_f32 v[22:23], v[20:21], v[30:31]
	v_fmac_f32_e32 v40, v27, v27
	v_fmac_f32_e32 v40, v22, v22
	v_fmac_f32_e32 v40, v23, v23
	v_cvt_pk_bf16_f32 v20, v24, v25
	v_cvt_pk_bf16_f32 v21, v26, v27
	v_cvt_pk_bf16_f32 v22, v22, v23
	v_cvt_pk_bf16_f32 v23, v28, v29
	v_fmac_f32_e32 v40, v28, v28
	global_store_dwordx4 v[36:37], v[20:23], off offset:256
	v_fmac_f32_e32 v40, v29, v29
	s_waitcnt vmcnt(7)
	v_lshlrev_b32_e32 v24, 16, v74
	v_lshlrev_b32_e32 v22, 16, v72
	v_and_b32_e32 v23, 0xffff0000, v72
	v_and_b32_e32 v25, 0xffff0000, v74
	v_lshlrev_b32_e32 v28, 16, v75
	v_and_b32_e32 v29, 0xffff0000, v75
	v_pk_add_f32 v[16:17], v[16:17], v[22:23]
	v_lshlrev_b32_e32 v26, 16, v73
	v_and_b32_e32 v27, 0xffff0000, v73
	v_pk_add_f32 v[22:23], v[14:15], v[28:29]
	v_pk_add_f32 v[14:15], v[12:13], v[24:25]
	v_fma_f32 v24, v16, v16, 0
	v_pk_add_f32 v[18:19], v[18:19], v[26:27]
	v_fmac_f32_e32 v24, v17, v17
	v_fmac_f32_e32 v24, v18, v18
	v_fmac_f32_e32 v24, v19, v19
	v_lshl_add_u64 v[20:21], s[8:9], 0, v[94:95]
	v_fmac_f32_e32 v24, v14, v14
	v_lshl_add_u64 v[20:21], v[20:21], 0, v[156:157]
	v_fmac_f32_e32 v24, v15, v15
	v_cvt_pk_bf16_f32 v12, v16, v17
	v_cvt_pk_bf16_f32 v13, v18, v19
	v_fmac_f32_e32 v24, v22, v22
	v_cvt_pk_bf16_f32 v14, v14, v15
	v_cvt_pk_bf16_f32 v15, v22, v23
	global_store_dwordx4 v[20:21], v[12:15], off
	v_fmac_f32_e32 v24, v23, v23
	s_waitcnt vmcnt(7)
	v_lshlrev_b32_e32 v16, 16, v69
	v_lshlrev_b32_e32 v12, 16, v68
	v_and_b32_e32 v13, 0xffff0000, v68
	v_pk_add_f32 v[8:9], v[8:9], v[12:13]
	v_and_b32_e32 v17, 0xffff0000, v69
	v_fmac_f32_e32 v24, v8, v8
	v_pk_add_f32 v[10:11], v[10:11], v[16:17]
	v_fmac_f32_e32 v24, v9, v9
	v_lshlrev_b32_e32 v14, 16, v70
	v_and_b32_e32 v15, 0xffff0000, v70
	v_lshlrev_b32_e32 v18, 16, v71
	v_and_b32_e32 v19, 0xffff0000, v71
	v_fmac_f32_e32 v24, v10, v10
	v_pk_add_f32 v[12:13], v[6:7], v[18:19]
	v_pk_add_f32 v[6:7], v[4:5], v[14:15]
	v_fmac_f32_e32 v24, v11, v11
	v_fmac_f32_e32 v24, v6, v6
	v_fmac_f32_e32 v24, v7, v7
	v_fmac_f32_e32 v24, v12, v12
	v_cvt_pk_bf16_f32 v4, v8, v9
	v_mov_b32_e32 v8, v40
	v_fmac_f32_e32 v24, v13, v13
	v_cvt_pk_bf16_f32 v5, v10, v11
	v_cvt_pk_bf16_f32 v6, v6, v7
	s_nop 0
	v_permlane16_swap_b32_e32 v40, v8
	v_cvt_pk_bf16_f32 v7, v12, v13
	global_store_dwordx4 v[20:21], v[4:7], off offset:256
	v_add_f32_e32 v10, v40, v8
	v_mov_b32_e32 v8, v24
	v_mov_b32_e32 v4, v60
	v_mov_b32_e32 v6, v44
	s_nop 0
	v_permlane16_swap_b32_e32 v60, v4
	v_permlane16_swap_b32_e32 v44, v6
	v_permlane16_swap_b32_e32 v24, v8
	v_add_f32_e32 v4, v60, v4
	v_add_f32_e32 v6, v44, v6
	v_add_f32_e32 v8, v24, v8
	v_mov_b32_e32 v5, v4
	v_mov_b32_e32 v7, v6
	v_mov_b32_e32 v11, v10
	v_mov_b32_e32 v9, v8
	v_permlane32_swap_b32_e32 v4, v5
	v_permlane32_swap_b32_e32 v6, v7
	v_permlane32_swap_b32_e32 v10, v11
	v_permlane32_swap_b32_e32 v8, v9
	s_and_saveexec_b64 s[0:1], vcc
	s_xor_b64 s[0:1], exec, s[0:1]
	s_cbranch_execz .LBB0_796
	v_cmp_gt_i32_e32 vcc, 3, v183
	s_and_saveexec_b64 s[6:7], vcc
	v_mov_b32_e32 v8, v10
	v_mov_b32_e32 v9, v11
	s_or_b64 exec, exec, s[6:7]

; __device__ __forceinline__ unsigned cvt_pk_bf16(float lo, float hi) { unsigned r; asm volatile("v_cvt_pk_bf16_f32 %0, %1, %2" : "=v"(r) : "v"(lo), "v"(hi)); return r; }
;     __device__ __forceinline__ void operator()(const f32x4 (&acc)[2][2][4][2], const Unit& u, int wr, int wc, int fr, int fq) const {
;     ...
;         for (int ai = 0; ai < 2; ++ai)
; #pragma unroll
;             for (int m = 0; m < 4; ++m) { bf16_t* rowp = base + (size_t)(row0 + ai * HALF + m * 16) * ldc + col0;
; #pragma unroll
;                 for (int bj = 0; bj < 2; ++bj) { f32x4 v0 = acc[ai][bj][m][0], v1 = acc[ai][bj][m][1];
;                     if (ACT == 2) {
; #pragma unroll
;                         for (int e = 0; e < 4; ++e) { const float a = fmaxf(v0[e], 0.f), b = fmaxf(v1[e], 0.f); v0[e] = a * a; v1[e] = b * b; } }
;                     u32x4 w; w.x = cvt_pk_bf16(v0[0], v0[1]); w.y = cvt_pk_bf16(v0[2], v0[3]); w.z = cvt_pk_bf16(v1[0], v1[1]); w.w = cvt_pk_bf16(v1[2], v1[3]);
;                     *(u32x4*)(rowp + bj * HALF) = w; } }
.LBB0_882:
	v_max_f32_e32 v124, 0, v124
	v_lshl_or_b32 v132, s43, 8, v138
	v_lshl_add_u32 v142, s44, 8, v137
	v_mul_f32_e32 v141, v124, v124
	v_max_f32_e32 v125, 0, v125
	v_max_f32_e32 v126, 0, v126
	v_ashrrev_i32_e32 v133, 31, v132
	v_ashrrev_i32_e32 v143, 31, v142
	v_max_f32_e32 v124, 0, v129
	v_mul_f32_e32 v129, v125, v125
	v_max_f32_e32 v125, v130, v130
	v_mul_f32_e32 v130, v126, v126
	v_lshl_add_u64 v[144:145], v[132:133], 1, s[6:7]
	v_lshlrev_b64 v[132:133], 14, v[142:143]
	v_max_f32_e32 v128, 0, v128
	v_mul_f32_e32 v124, v124, v124
	v_max_f32_e32 v125, 0, v125
	v_max_f32_e32 v126, 0, v131
	v_max_f32_e32 v127, 0, v127
	v_lshl_add_u64 v[132:133], v[144:145], 0, v[132:133]
	v_mul_f32_e32 v128, v128, v128
	v_mul_f32_e32 v125, v125, v125
	v_mul_f32_e32 v126, v126, v126
	v_mul_f32_e32 v127, v127, v127
	v_cvt_pk_bf16_f32 v124, v128, v124
	v_max_f32_e32 v116, 0, v116
	v_max_f32_e32 v117, 0, v117
	v_max_f32_e32 v118, 0, v118
	v_cvt_pk_bf16_f32 v125, v125, v126
	v_cvt_pk_bf16_f32 v126, v141, v129
	v_cvt_pk_bf16_f32 v127, v130, v127
	global_store_dwordx4 v[132:133], v[124:127], off
	s_nop 1
	v_mul_f32_e32 v124, v116, v116
	v_max_f32_e32 v116, v121, v121
	v_mul_f32_e32 v121, v117, v117
	v_max_f32_e32 v117, v122, v122
	v_mul_f32_e32 v122, v118, v118
	v_max_f32_e32 v116, 0, v116
	v_max_f32_e32 v117, 0, v117
	v_max_f32_e32 v118, 0, v123
	v_max_f32_e32 v120, 0, v120
	v_mul_f32_e32 v116, v116, v116
	v_mul_f32_e32 v117, v117, v117
	v_max_f32_e32 v119, 0, v119
	v_mul_f32_e32 v118, v118, v118
	v_mul_f32_e32 v120, v120, v120
	v_mul_f32_e32 v119, v119, v119
	v_cvt_pk_bf16_f32 v116, v120, v116
	v_cvt_pk_bf16_f32 v117, v117, v118
	v_cvt_pk_bf16_f32 v118, v124, v121
	v_max_f32_e32 v108, 0, v108
	v_cvt_pk_bf16_f32 v119, v122, v119
	global_store_dwordx4 v[132:133], v[116:119], off offset:256
	v_max_f32_e32 v109, 0, v109
	v_max_f32_e32 v110, 0, v110
	v_or_b32_e32 v116, 16, v142
	v_mul_f32_e32 v118, v108, v108
	v_ashrrev_i32_e32 v117, 31, v116
	v_max_f32_e32 v108, 0, v113
	v_mul_f32_e32 v113, v109, v109
	v_max_f32_e32 v109, v114, v114
	v_mul_f32_e32 v114, v110, v110
	v_lshlrev_b64 v[116:117], 14, v[116:117]
	v_max_f32_e32 v112, 0, v112
	v_mul_f32_e32 v108, v108, v108
	v_max_f32_e32 v109, 0, v109
	v_max_f32_e32 v110, 0, v115
	v_max_f32_e32 v111, 0, v111
	v_lshl_add_u64 v[116:117], v[144:145], 0, v[116:117]
	v_mul_f32_e32 v112, v112, v112
	v_mul_f32_e32 v109, v109, v109
	v_mul_f32_e32 v110, v110, v110
	v_mul_f32_e32 v111, v111, v111
	v_cvt_pk_bf16_f32 v108, v112, v108
	v_max_f32_e32 v100, 0, v100
	v_max_f32_e32 v101, 0, v101
	v_max_f32_e32 v102, 0, v102
	v_cvt_pk_bf16_f32 v109, v109, v110
	v_cvt_pk_bf16_f32 v110, v118, v113
	v_cvt_pk_bf16_f32 v111, v114, v111
	global_store_dwordx4 v[116:117], v[108:111], off
	s_nop 1
	v_mul_f32_e32 v108, v100, v100
	v_max_f32_e32 v100, v105, v105
	v_mul_f32_e32 v105, v101, v101
	v_max_f32_e32 v101, v106, v106
	v_mul_f32_e32 v106, v102, v102
	v_max_f32_e32 v100, 0, v100
	v_max_f32_e32 v101, 0, v101
	v_max_f32_e32 v102, 0, v107
	v_max_f32_e32 v104, 0, v104
	v_mul_f32_e32 v100, v100, v100
	v_mul_f32_e32 v101, v101, v101
	v_max_f32_e32 v103, 0, v103
	v_mul_f32_e32 v102, v102, v102
	v_mul_f32_e32 v104, v104, v104
	v_mul_f32_e32 v103, v103, v103
	v_cvt_pk_bf16_f32 v100, v104, v100
	v_cvt_pk_bf16_f32 v101, v101, v102
	v_cvt_pk_bf16_f32 v102, v108, v105
	v_max_f32_e32 v92, 0, v92
	v_cvt_pk_bf16_f32 v103, v106, v103
	global_store_dwordx4 v[116:117], v[100:103], off offset:256
	v_max_f32_e32 v93, 0, v93
	v_max_f32_e32 v94, 0, v94
	v_or_b32_e32 v100, 32, v142
	v_mul_f32_e32 v102, v92, v92
	v_ashrrev_i32_e32 v101, 31, v100
	v_max_f32_e32 v92, 0, v97
	v_mul_f32_e32 v97, v93, v93
	v_max_f32_e32 v93, v98, v98
	v_mul_f32_e32 v98, v94, v94
	v_lshlrev_b64 v[100:101], 14, v[100:101]
	v_max_f32_e32 v96, 0, v96
	v_mul_f32_e32 v92, v92, v92
	v_max_f32_e32 v93, 0, v93
	v_max_f32_e32 v94, 0, v99
	v_max_f32_e32 v95, 0, v95
	v_lshl_add_u64 v[100:101], v[144:145], 0, v[100:101]
	v_mul_f32_e32 v96, v96, v96
	v_mul_f32_e32 v93, v93, v93
	v_mul_f32_e32 v94, v94, v94
	v_mul_f32_e32 v95, v95, v95
	v_cvt_pk_bf16_f32 v92, v96, v92
	v_max_f32_e32 v84, 0, v84
	v_max_f32_e32 v85, 0, v85
	v_max_f32_e32 v86, 0, v86
	v_cvt_pk_bf16_f32 v93, v93, v94
	v_cvt_pk_bf16_f32 v94, v102, v97
	v_cvt_pk_bf16_f32 v95, v98, v95
	global_store_dwordx4 v[100:101], v[92:95], off
	s_nop 1
	v_mul_f32_e32 v92, v84, v84
	v_max_f32_e32 v84, v89, v89
	v_mul_f32_e32 v89, v85, v85
	v_max_f32_e32 v85, v90, v90
	v_mul_f32_e32 v90, v86, v86
	v_max_f32_e32 v84, 0, v84
	v_max_f32_e32 v85, 0, v85
	v_max_f32_e32 v86, 0, v91
	v_max_f32_e32 v88, 0, v88
	v_mul_f32_e32 v84, v84, v84
	v_mul_f32_e32 v85, v85, v85
	v_max_f32_e32 v87, 0, v87
	v_mul_f32_e32 v86, v86, v86
	v_mul_f32_e32 v88, v88, v88
	v_mul_f32_e32 v87, v87, v87
	v_cvt_pk_bf16_f32 v84, v88, v84
	v_cvt_pk_bf16_f32 v85, v85, v86
	v_cvt_pk_bf16_f32 v86, v92, v89
	v_max_f32_e32 v76, 0, v76
	v_cvt_pk_bf16_f32 v87, v90, v87
	global_store_dwordx4 v[100:101], v[84:87], off offset:256
	v_max_f32_e32 v77, 0, v77
	v_max_f32_e32 v78, 0, v78
	v_or_b32_e32 v84, 48, v142
	v_mul_f32_e32 v86, v76, v76
	v_ashrrev_i32_e32 v85, 31, v84
	v_max_f32_e32 v76, 0, v81
	v_mul_f32_e32 v81, v77, v77
	v_max_f32_e32 v77, v82, v82
	v_mul_f32_e32 v82, v78, v78
	v_lshlrev_b64 v[84:85], 14, v[84:85]
	v_max_f32_e32 v80, 0, v80
	v_mul_f32_e32 v76, v76, v76
	v_max_f32_e32 v77, 0, v77
	v_max_f32_e32 v78, 0, v83
	v_max_f32_e32 v79, 0, v79
	v_lshl_add_u64 v[84:85], v[144:145], 0, v[84:85]
	v_mul_f32_e32 v80, v80, v80
	v_mul_f32_e32 v77, v77, v77
	v_mul_f32_e32 v78, v78, v78
	v_mul_f32_e32 v79, v79, v79
	v_cvt_pk_bf16_f32 v76, v80, v76
	v_max_f32_e32 v68, 0, v68
	v_max_f32_e32 v69, 0, v69
; __device__ __forceinline__ unsigned cvt_pk_bf16(float lo, float hi) { unsigned r; asm volatile("v_cvt_pk_bf16_f32 %0, %1, %2" : "=v"(r) : "v"(lo), "v"(hi)); return r; }
;     __device__ __forceinline__ void operator()(const f32x4 (&acc)[2][2][4][2], const Unit& u, int wr, int wc, int fr, int fq) const {
;     ...
;         for (int ai = 0; ai < 2; ++ai)
; #pragma unroll
;             for (int m = 0; m < 4; ++m) { bf16_t* rowp = base + (size_t)(row0 + ai * HALF + m * 16) * ldc + col0;
; #pragma unroll
;                 for (int bj = 0; bj < 2; ++bj) { f32x4 v0 = acc[ai][bj][m][0], v1 = acc[ai][bj][m][1];
;                     if (ACT == 2) {
; #pragma unroll
;                         for (int e = 0; e < 4; ++e) { const float a = fmaxf(v0[e], 0.f), b = fmaxf(v1[e], 0.f); v0[e] = a * a; v1[e] = b * b; } }
;                     u32x4 w; w.x = cvt_pk_bf16(v0[0], v0[1]); w.y = cvt_pk_bf16(v0[2], v0[3]); w.z = cvt_pk_bf16(v1[0], v1[1]); w.w = cvt_pk_bf16(v1[2], v1[3]);
;                     *(u32x4*)(rowp + bj * HALF) = w; } }
	v_max_f32_e32 v70, 0, v70
	v_cvt_pk_bf16_f32 v77, v77, v78
	v_cvt_pk_bf16_f32 v78, v86, v81
	v_cvt_pk_bf16_f32 v79, v82, v79
	global_store_dwordx4 v[84:85], v[76:79], off
	s_nop 1
	v_mul_f32_e32 v76, v68, v68
	v_max_f32_e32 v68, v73, v73
	v_mul_f32_e32 v73, v69, v69
	v_max_f32_e32 v69, v74, v74
	v_mul_f32_e32 v74, v70, v70
	v_max_f32_e32 v68, 0, v68
	v_max_f32_e32 v69, 0, v69
	v_max_f32_e32 v70, 0, v75
	v_max_f32_e32 v72, 0, v72
	v_mul_f32_e32 v68, v68, v68
	v_mul_f32_e32 v69, v69, v69
	v_max_f32_e32 v71, 0, v71
	v_mul_f32_e32 v70, v70, v70
	v_mul_f32_e32 v72, v72, v72
	v_mul_f32_e32 v71, v71, v71
	v_cvt_pk_bf16_f32 v68, v72, v68
	v_cvt_pk_bf16_f32 v69, v69, v70
	v_cvt_pk_bf16_f32 v70, v76, v73
	v_max_f32_e32 v60, 0, v60
	v_cvt_pk_bf16_f32 v71, v74, v71
	global_store_dwordx4 v[84:85], v[68:71], off offset:256
	s_nop 0
	v_max_f32_e32 v61, 0, v61
	v_mul_f32_e32 v70, v60, v60
	v_max_f32_e32 v62, 0, v62
	s_mov_b64 s[0:1], 0x200000
	v_max_f32_e32 v64, 0, v64
	v_max_f32_e32 v60, 0, v65
	v_mul_f32_e32 v65, v61, v61
	v_max_f32_e32 v61, v66, v66
	v_mul_f32_e32 v66, v62, v62
	v_lshl_add_u64 v[68:69], v[132:133], 0, s[0:1]
	v_mul_f32_e32 v64, v64, v64
	v_mul_f32_e32 v60, v60, v60
	v_max_f32_e32 v61, 0, v61
	v_max_f32_e32 v62, 0, v67
	s_mov_b32 s0, 0x200000
	v_mul_f32_e32 v61, v61, v61
	v_max_f32_e32 v63, 0, v63
	v_mul_f32_e32 v62, v62, v62
	v_cvt_pk_bf16_f32 v60, v64, v60
	v_add_co_u32_e32 v64, vcc, s0, v132
	v_mul_f32_e32 v63, v63, v63
	v_cvt_pk_bf16_f32 v61, v61, v62
	v_cvt_pk_bf16_f32 v62, v70, v65
	v_addc_co_u32_e32 v65, vcc, 0, v133, vcc
	v_max_f32_e32 v52, 0, v52
	v_max_f32_e32 v53, 0, v53
	v_max_f32_e32 v54, 0, v54
	v_cvt_pk_bf16_f32 v63, v66, v63
	global_store_dwordx4 v[64:65], v[60:63], off
	s_nop 1
	v_mul_f32_e32 v60, v52, v52
	v_max_f32_e32 v52, v57, v57
	v_mul_f32_e32 v57, v53, v53
	v_max_f32_e32 v53, v58, v58
	v_mul_f32_e32 v58, v54, v54
	v_max_f32_e32 v52, 0, v52
	v_max_f32_e32 v53, 0, v53
	v_max_f32_e32 v54, 0, v59
	v_max_f32_e32 v56, 0, v56
	v_mul_f32_e32 v52, v52, v52
	v_mul_f32_e32 v53, v53, v53
	v_max_f32_e32 v55, 0, v55
	v_mul_f32_e32 v54, v54, v54
	v_mul_f32_e32 v56, v56, v56
	v_mul_f32_e32 v55, v55, v55
	v_cvt_pk_bf16_f32 v52, v56, v52
	v_cvt_pk_bf16_f32 v53, v53, v54
	v_cvt_pk_bf16_f32 v54, v60, v57
	v_max_f32_e32 v44, 0, v44
	v_cvt_pk_bf16_f32 v55, v58, v55
	global_store_dwordx4 v[68:69], v[52:55], off offset:256
	s_nop 0
	v_max_f32_e32 v45, 0, v45
	v_mul_f32_e32 v54, v44, v44
	v_max_f32_e32 v46, 0, v46
	s_mov_b64 s[0:1], 0x240000
	v_max_f32_e32 v48, 0, v48
	v_max_f32_e32 v44, 0, v49
	v_mul_f32_e32 v49, v45, v45
	v_max_f32_e32 v45, v50, v50
	v_mul_f32_e32 v50, v46, v46
	v_lshl_add_u64 v[52:53], v[132:133], 0, s[0:1]
	v_mul_f32_e32 v48, v48, v48
	v_mul_f32_e32 v44, v44, v44
	v_max_f32_e32 v45, 0, v45
	v_max_f32_e32 v46, 0, v51
	s_mov_b32 s0, 0x240000
	v_mul_f32_e32 v45, v45, v45
	v_max_f32_e32 v47, 0, v47
	v_mul_f32_e32 v46, v46, v46
	v_cvt_pk_bf16_f32 v44, v48, v44
	v_add_co_u32_e32 v48, vcc, s0, v132
	v_mul_f32_e32 v47, v47, v47
	v_cvt_pk_bf16_f32 v45, v45, v46
	v_cvt_pk_bf16_f32 v46, v54, v49
	v_addc_co_u32_e32 v49, vcc, 0, v133, vcc
	v_max_f32_e32 v36, 0, v36
	v_max_f32_e32 v37, 0, v37
	v_max_f32_e32 v38, 0, v38
	v_cvt_pk_bf16_f32 v47, v50, v47
	global_store_dwordx4 v[48:49], v[44:47], off
	s_nop 1
	v_mul_f32_e32 v44, v36, v36
	v_max_f32_e32 v36, v41, v41
	v_mul_f32_e32 v41, v37, v37
	v_max_f32_e32 v37, v42, v42
	v_mul_f32_e32 v42, v38, v38
	v_max_f32_e32 v36, 0, v36
	v_max_f32_e32 v37, 0, v37
	v_max_f32_e32 v38, 0, v43
	v_max_f32_e32 v40, 0, v40
	v_mul_f32_e32 v36, v36, v36
	v_mul_f32_e32 v37, v37, v37
	v_max_f32_e32 v39, 0, v39
	v_mul_f32_e32 v38, v38, v38
	v_mul_f32_e32 v40, v40, v40
	v_mul_f32_e32 v39, v39, v39
	v_cvt_pk_bf16_f32 v36, v40, v36
	v_cvt_pk_bf16_f32 v37, v37, v38
	v_cvt_pk_bf16_f32 v38, v44, v41
	v_max_f32_e32 v28, 0, v28
	v_cvt_pk_bf16_f32 v39, v42, v39
	global_store_dwordx4 v[52:53], v[36:39], off offset:256
	s_nop 0
	v_max_f32_e32 v29, 0, v29
	v_mul_f32_e32 v38, v28, v28
	v_max_f32_e32 v30, 0, v30
	s_mov_b64 s[0:1], 0x280000
	v_max_f32_e32 v32, 0, v32
	v_max_f32_e32 v28, 0, v33
	v_mul_f32_e32 v33, v29, v29
	v_max_f32_e32 v29, v34, v34
	v_mul_f32_e32 v34, v30, v30
	v_lshl_add_u64 v[36:37], v[132:133], 0, s[0:1]
	v_mul_f32_e32 v32, v32, v32
	v_mul_f32_e32 v28, v28, v28
	v_max_f32_e32 v29, 0, v29
	v_max_f32_e32 v30, 0, v35
	s_mov_b32 s0, 0x280000
	v_mul_f32_e32 v29, v29, v29
	v_max_f32_e32 v31, 0, v31
	v_mul_f32_e32 v30, v30, v30
	v_cvt_pk_bf16_f32 v28, v32, v28
	v_add_co_u32_e32 v32, vcc, s0, v132
	v_mul_f32_e32 v31, v31, v31
	v_cvt_pk_bf16_f32 v29, v29, v30
	v_cvt_pk_bf16_f32 v30, v38, v33
	v_addc_co_u32_e32 v33, vcc, 0, v133, vcc
	v_max_f32_e32 v20, 0, v20
	v_max_f32_e32 v21, 0, v21
	v_max_f32_e32 v22, 0, v22
	v_cvt_pk_bf16_f32 v31, v34, v31
	global_store_dwordx4 v[32:33], v[28:31], off
	s_nop 1
	v_mul_f32_e32 v28, v20, v20
	v_max_f32_e32 v20, v25, v25
	v_mul_f32_e32 v25, v21, v21
	v_max_f32_e32 v21, v26, v26
	v_mul_f32_e32 v26, v22, v22
	v_max_f32_e32 v20, 0, v20
	v_max_f32_e32 v21, 0, v21
	v_max_f32_e32 v22, 0, v27
	v_max_f32_e32 v24, 0, v24
	v_mul_f32_e32 v20, v20, v20
	v_mul_f32_e32 v21, v21, v21
	v_max_f32_e32 v23, 0, v23
	v_mul_f32_e32 v22, v22, v22
	v_mul_f32_e32 v24, v24, v24
	v_mul_f32_e32 v23, v23, v23
	v_cvt_pk_bf16_f32 v20, v24, v20
	v_cvt_pk_bf16_f32 v21, v21, v22
	v_cvt_pk_bf16_f32 v22, v28, v25
	v_max_f32_e32 v12, 0, v12
	v_cvt_pk_bf16_f32 v23, v26, v23
	global_store_dwordx4 v[36:37], v[20:23], off offset:256
	s_nop 0
	v_max_f32_e32 v13, 0, v13
	v_mul_f32_e32 v22, v12, v12
	v_max_f32_e32 v14, 0, v14
	s_mov_b64 s[0:1], 0x2c0000
	v_max_f32_e32 v16, 0, v16
	v_max_f32_e32 v12, 0, v17
	v_mul_f32_e32 v17, v13, v13
	v_max_f32_e32 v13, v18, v18
	v_mul_f32_e32 v18, v14, v14
	v_lshl_add_u64 v[20:21], v[132:133], 0, s[0:1]
	v_mul_f32_e32 v16, v16, v16
	v_mul_f32_e32 v12, v12, v12
	v_max_f32_e32 v13, 0, v13
	v_max_f32_e32 v14, 0, v19
	s_mov_b32 s0, 0x2c0000
	v_mul_f32_e32 v13, v13, v13
	v_max_f32_e32 v15, 0, v15
	v_mul_f32_e32 v14, v14, v14
	v_cvt_pk_bf16_f32 v12, v16, v12
	v_add_co_u32_e32 v16, vcc, s0, v132
	v_mul_f32_e32 v15, v15, v15
	v_cvt_pk_bf16_f32 v13, v13, v14
	v_cvt_pk_bf16_f32 v14, v22, v17
	v_addc_co_u32_e32 v17, vcc, 0, v133, vcc
	v_max_f32_e32 v4, 0, v4
	v_max_f32_e32 v5, 0, v5
	v_max_f32_e32 v6, 0, v6
	v_cvt_pk_bf16_f32 v15, v18, v15
	global_store_dwordx4 v[16:17], v[12:15], off
	s_nop 1
	v_mul_f32_e32 v12, v4, v4
	v_max_f32_e32 v4, v9, v9
	v_mul_f32_e32 v9, v5, v5
	v_max_f32_e32 v5, v10, v10
	v_mul_f32_e32 v10, v6, v6
	v_max_f32_e32 v4, 0, v4
	v_max_f32_e32 v5, 0, v5
	v_max_f32_e32 v6, 0, v11
	v_max_f32_e32 v7, 0, v7
	v_max_f32_e32 v8, 0, v8
	v_mul_f32_e32 v4, v4, v4
	v_mul_f32_e32 v5, v5, v5
	v_mul_f32_e32 v6, v6, v6
	v_mul_f32_e32 v7, v7, v7
	v_mul_f32_e32 v8, v8, v8
	v_cvt_pk_bf16_f32 v4, v8, v4
	v_cvt_pk_bf16_f32 v5, v5, v6
	v_cvt_pk_bf16_f32 v6, v12, v9
	v_cvt_pk_bf16_f32 v7, v10, v7
	s_andn2_b64 vcc, exec, s[4:5]
	s_mov_b64 s[0:1], -1
	global_store_dwordx4 v[20:21], v[4:7], off offset:256
	s_cbranch_vccnz .LBB0_871
; #define PG8_BAR __builtin_amdgcn_s_barrier()
; template <class Epi, class Sched, bool ALIGN_EPI = false, bool SP2 = false>
; __device__ __forceinline__ void gemm_phase(PG8_LAS unsigned char* lds, const Gemm g, const Sched& S, const Epi& E) {
;     ...
; #pragma unroll
;         for (int a = 0; a < 2; ++a)
; #pragma unroll
;             for (int b = 0; b < 2; ++b)
; #pragma unroll
;                 for (int m = 0; m < 4; ++m)
; #pragma unroll
;                     for (int n = 0; n < 2; ++n) { typedef double d2_t __attribute__((ext_vector_type(2))); d2_t z; double z0, z1;
;                         asm volatile("v_mov_b64 %0, 0" : "=v"(z0)); asm volatile("v_mov_b64 %0, 0" : "=v"(z1)); z.x = z0; z.y = z1; acc[a][b][m][n] = __builtin_bit_cast(f32x4, z); }
;         cur = nxt; cA = nA; cB = nB; ++ui;
;         if constexpr (ALIGN_EPI) { if (wr == 1) PG8_BAR; }
	s_andn2_b64 vcc, exec, s[2:3]
	v_mov_b64 v[128:129], 0
	v_mov_b64 v[130:131], 0
	v_mov_b64 v[124:125], 0
	v_mov_b64 v[126:127], 0
	v_mov_b64 v[112:113], 0
	v_mov_b64 v[114:115], 0
	v_mov_b64 v[108:109], 0
	v_mov_b64 v[110:111], 0
	v_mov_b64 v[96:97], 0
	v_mov_b64 v[98:99], 0
	v_mov_b64 v[92:93], 0
	v_mov_b64 v[94:95], 0
	v_mov_b64 v[80:81], 0
	v_mov_b64 v[82:83], 0
	v_mov_b64 v[76:77], 0
	v_mov_b64 v[78:79], 0
	v_mov_b64 v[120:121], 0
	v_mov_b64 v[122:123], 0
	v_mov_b64 v[116:117], 0
	v_mov_b64 v[118:119], 0
	v_mov_b64 v[104:105], 0
	v_mov_b64 v[106:107], 0
	v_mov_b64 v[100:101], 0
	v_mov_b64 v[102:103], 0
	v_mov_b64 v[88:89], 0
	v_mov_b64 v[90:91], 0
	v_mov_b64 v[84:85], 0
	v_mov_b64 v[86:87], 0
	v_mov_b64 v[72:73], 0
	v_mov_b64 v[74:75], 0
	v_mov_b64 v[68:69], 0
	v_mov_b64 v[70:71], 0
	v_mov_b64 v[64:65], 0
	v_mov_b64 v[66:67], 0
	v_mov_b64 v[60:61], 0
	v_mov_b64 v[62:63], 0
	v_mov_b64 v[48:49], 0
	v_mov_b64 v[50:51], 0
	v_mov_b64 v[44:45], 0
	v_mov_b64 v[46:47], 0
	v_mov_b64 v[32:33], 0
	v_mov_b64 v[34:35], 0
	v_mov_b64 v[28:29], 0
	v_mov_b64 v[30:31], 0
	v_mov_b64 v[16:17], 0
	v_mov_b64 v[18:19], 0
	v_mov_b64 v[12:13], 0
	v_mov_b64 v[14:15], 0
	v_mov_b64 v[56:57], 0
	v_mov_b64 v[58:59], 0
	v_mov_b64 v[52:53], 0
	v_mov_b64 v[54:55], 0
	v_mov_b64 v[40:41], 0
	v_mov_b64 v[42:43], 0
	v_mov_b64 v[36:37], 0
	v_mov_b64 v[38:39], 0
	v_mov_b64 v[24:25], 0
	v_mov_b64 v[26:27], 0
	v_mov_b64 v[20:21], 0
	v_mov_b64 v[22:23], 0
	v_mov_b64 v[8:9], 0
	v_mov_b64 v[10:11], 0
	v_mov_b64 v[4:5], 0
	v_mov_b64 v[6:7], 0
	s_cbranch_vccnz .LBB0_870
	s_barrier
	s_branch .LBB0_870
